# P4b: 3 of the 4 sample sequences per scan workgroup moved to the branch-B workgroups (after zb_rows), scan workgroups keep 1
# speedup vs baseline: 1.0022x; 1.0019x over previous
; #define LDSBAR() do { asm volatile("s_waitcnt lgkmcnt(0)" ::: "memory"); __builtin_amdgcn_s_barrier(); asm volatile("" ::: "memory"); } while (0)
; #define HG_STORE(R, s) do { LAS unsigned char* d_ = ring + (s) * HG_SLOT; *(LAS v4u*)(d_ + 16 * tid) = R.q; if (vload) *(LAS v4u*)(d_ + 16384 + 16 * tid) = R.v; *(LAS v4u*)(d_ + 8192 + 16 * tid) = R.l0; \
;         if (tid < 160) *(LAS v4u*)(d_ + 24576 + 16 * tid) = R.l1; } while (0)
; __device__ __forceinline__ void hg_seq(const Frame& F, unsigned char* ws, const float* s0, float* sout, float* Og, int seq, bool sample, int vs_base, int nvs) {
;     ...
;     if (!sample) { const int b = seq >> 2; h = seq & 3; t0 = b * 2048; nch = 64; nvalid = 32; const size_t e0 = (size_t)t0 * DA + h * 128;
;         qf = ws + WS_Q + e0 * 2; vf = ws + WS_V + e0 * 2; lf = ws + WS_LOGF + e0 * 4; qp = 1024; lp = 2048; qstep = 32 * 1024; lstep = 32 * 2048; }
;     else { const int b = seq >> 2; h = seq & 3; t0 = TP + b * 8; nch = 1; nvalid = 8; const unsigned char* base = (const unsigned char*)sout + (size_t)seq * 65536;
;         qf = base; vf = base + 8192; lf = base + 16384; qp = 256; lp = 512; qstep = 0; lstep = 0; }
;     const size_t offq = (size_t)(tid >> 4) * qp + (tid & 15) * 16, offl0 = (size_t)(tid >> 5) * lp + (tid & 31) * 16, offl1 = (size_t)(16 + (tid >> 5)) * lp + (tid & 31) * 16, offl1c = tid < 160 ? offl1 : offl0;
;     {
;     f32x4 S[8];
;     if (sample && active) {
; #pragma unroll
;         for (int kb = 0; kb < 8; ++kb)
; #pragma unroll
;             for (int i = 0; i < 4; ++i) S[kb][i] = s0[((size_t)seq * 128 + 16 * kb + 4 * q + i) * 128 + 16 * vs + r];
;     } else {
; #pragma unroll
;         for (int kb = 0; kb < 8; ++kb) S[kb] = (f32x4){0.f, 0.f, 0.f, 0.f};
;     }
;     float* Ob = Og + (size_t)t0 * DA + h * 128;
;     ...
;     HgPre R0, R1, R2, R3, R4, R5;
;     R0.l1 = R0.v = (v4u){0u, 0u, 0u, 0u}; R1.l1 = R1.v = (v4u){0u, 0u, 0u, 0u}; R2.l1 = R2.v = (v4u){0u, 0u, 0u, 0u}; R3.l1 = R3.v = (v4u){0u, 0u, 0u, 0u}; R4.l1 = R4.v = (v4u){0u, 0u, 0u, 0u}; R5.l1 = R5.v = (v4u){0u, 0u, 0u, 0u};
;     HG_LOAD(R0, 0); HG_LOAD(R1, 1); HG_LOAD(R2, 2); HG_LOAD(R3, 3); HG_LOAD(R4, 4);
;     HG_STORE(R0, 0); LDSBAR();
.Lsmpa_p4_done:
	s_add_u32 s6, s10, s36
	s_addc_u32 s7, s11, 0
	v_lshl_add_u64 v[140:141], s[6:7], 0, v[2:3]
	s_lshl_b32 s38, s50, 10
	s_add_i32 s39, s38, 0x4000
	s_add_i32 s40, s38, 0x2000
	s_mov_b32 m0, s38
	s_nop 0
	global_load_lds_dwordx4 v[210:211], off
	s_mov_b32 m0, s39
	s_nop 0
	global_load_lds_dwordx4 v[212:213], off
	s_mov_b32 m0, s40
	s_nop 0
	global_load_lds_dwordx4 v[214:215], off
	s_mov_b32 m0, s37
	s_nop 0
	global_load_lds_dwordx4 v[140:141], off
	global_load_dwordx4 v[4:7], v200, s[8:9]
	global_load_dwordx4 v[8:11], v201, s[8:9]
	global_load_dwordx4 v[12:15], v202, s[8:9]
	global_load_dwordx4 v[16:19], v203, s[8:9]
	global_load_dwordx4 v[20:23], v204, s[8:9]
	global_load_dwordx4 v[24:27], v205, s[8:9]
	global_load_dwordx4 v[28:31], v206, s[8:9]
	global_load_dwordx4 v[32:35], v207, s[8:9]
	s_add_u32 s8, s8, s34
	s_addc_u32 s9, s9, 0
	s_waitcnt vmcnt(0)
	s_barrier
	v_cndmask_b32_e64 v145, v4, v5, s[42:43]
	v_cndmask_b32_e64 v147, v6, v7, s[42:43]
	s_nop 1
	v_mov_b32_dpp v146, v145 quad_perm:[1,0,3,2] row_mask:0xf bank_mask:0xf
	v_mov_b32_dpp v156, v147 quad_perm:[1,0,3,2] row_mask:0xf bank_mask:0xf
	v_cndmask_b32_e64 v5, v5, v146, s[42:43]
	v_cndmask_b32_e64 v4, v146, v4, s[42:43]
	v_cndmask_b32_e64 v7, v7, v156, s[42:43]
	v_cndmask_b32_e64 v6, v156, v6, s[42:43]
	v_cndmask_b32_e64 v145, v4, v6, s[44:45]
	v_cndmask_b32_e64 v147, v5, v7, s[44:45]
	s_nop 1
	v_mov_b32_dpp v146, v145 quad_perm:[2,3,0,1] row_mask:0xf bank_mask:0xf
	v_mov_b32_dpp v156, v147 quad_perm:[2,3,0,1] row_mask:0xf bank_mask:0xf
	v_cndmask_b32_e64 v6, v6, v146, s[44:45]
	v_cndmask_b32_e64 v4, v146, v4, s[44:45]
	v_cndmask_b32_e64 v7, v7, v156, s[44:45]
	v_cndmask_b32_e64 v5, v156, v5, s[44:45]
	v_cndmask_b32_e64 v145, v8, v9, s[42:43]
	v_cndmask_b32_e64 v147, v10, v11, s[42:43]
	s_nop 1
	v_mov_b32_dpp v146, v145 quad_perm:[1,0,3,2] row_mask:0xf bank_mask:0xf
	v_mov_b32_dpp v156, v147 quad_perm:[1,0,3,2] row_mask:0xf bank_mask:0xf
	v_cndmask_b32_e64 v9, v9, v146, s[42:43]
	v_cndmask_b32_e64 v8, v146, v8, s[42:43]
	v_cndmask_b32_e64 v11, v11, v156, s[42:43]
	v_cndmask_b32_e64 v10, v156, v10, s[42:43]
	v_cndmask_b32_e64 v145, v8, v10, s[44:45]
	v_cndmask_b32_e64 v147, v9, v11, s[44:45]
	s_nop 1
	v_mov_b32_dpp v146, v145 quad_perm:[2,3,0,1] row_mask:0xf bank_mask:0xf
	v_mov_b32_dpp v156, v147 quad_perm:[2,3,0,1] row_mask:0xf bank_mask:0xf
	v_cndmask_b32_e64 v10, v10, v146, s[44:45]
	v_cndmask_b32_e64 v8, v146, v8, s[44:45]
	v_cndmask_b32_e64 v11, v11, v156, s[44:45]
	v_cndmask_b32_e64 v9, v156, v9, s[44:45]
	v_cndmask_b32_e64 v145, v12, v13, s[42:43]
	v_cndmask_b32_e64 v147, v14, v15, s[42:43]
	s_nop 1
	v_mov_b32_dpp v146, v145 quad_perm:[1,0,3,2] row_mask:0xf bank_mask:0xf
	v_mov_b32_dpp v156, v147 quad_perm:[1,0,3,2] row_mask:0xf bank_mask:0xf
	v_cndmask_b32_e64 v13, v13, v146, s[42:43]
	v_cndmask_b32_e64 v12, v146, v12, s[42:43]
	v_cndmask_b32_e64 v15, v15, v156, s[42:43]
	v_cndmask_b32_e64 v14, v156, v14, s[42:43]
	v_cndmask_b32_e64 v145, v12, v14, s[44:45]
	v_cndmask_b32_e64 v147, v13, v15, s[44:45]
	s_nop 1
	v_mov_b32_dpp v146, v145 quad_perm:[2,3,0,1] row_mask:0xf bank_mask:0xf
	v_mov_b32_dpp v156, v147 quad_perm:[2,3,0,1] row_mask:0xf bank_mask:0xf
	v_cndmask_b32_e64 v14, v14, v146, s[44:45]
	v_cndmask_b32_e64 v12, v146, v12, s[44:45]
	v_cndmask_b32_e64 v15, v15, v156, s[44:45]
	v_cndmask_b32_e64 v13, v156, v13, s[44:45]
	v_cndmask_b32_e64 v145, v16, v17, s[42:43]
	v_cndmask_b32_e64 v147, v18, v19, s[42:43]
	s_nop 1
	v_mov_b32_dpp v146, v145 quad_perm:[1,0,3,2] row_mask:0xf bank_mask:0xf
	v_mov_b32_dpp v156, v147 quad_perm:[1,0,3,2] row_mask:0xf bank_mask:0xf
	v_cndmask_b32_e64 v17, v17, v146, s[42:43]
	v_cndmask_b32_e64 v16, v146, v16, s[42:43]
	v_cndmask_b32_e64 v19, v19, v156, s[42:43]
	v_cndmask_b32_e64 v18, v156, v18, s[42:43]
	v_cndmask_b32_e64 v145, v16, v18, s[44:45]
	v_cndmask_b32_e64 v147, v17, v19, s[44:45]
	s_nop 1
	v_mov_b32_dpp v146, v145 quad_perm:[2,3,0,1] row_mask:0xf bank_mask:0xf
	v_mov_b32_dpp v156, v147 quad_perm:[2,3,0,1] row_mask:0xf bank_mask:0xf
	v_cndmask_b32_e64 v18, v18, v146, s[44:45]
	v_cndmask_b32_e64 v16, v146, v16, s[44:45]
	v_cndmask_b32_e64 v19, v19, v156, s[44:45]
	v_cndmask_b32_e64 v17, v156, v17, s[44:45]
	v_cndmask_b32_e64 v145, v20, v21, s[42:43]
	v_cndmask_b32_e64 v147, v22, v23, s[42:43]
	s_nop 1
	v_mov_b32_dpp v146, v145 quad_perm:[1,0,3,2] row_mask:0xf bank_mask:0xf
	v_mov_b32_dpp v156, v147 quad_perm:[1,0,3,2] row_mask:0xf bank_mask:0xf
	v_cndmask_b32_e64 v21, v21, v146, s[42:43]
	v_cndmask_b32_e64 v20, v146, v20, s[42:43]
	v_cndmask_b32_e64 v23, v23, v156, s[42:43]
	v_cndmask_b32_e64 v22, v156, v22, s[42:43]
	v_cndmask_b32_e64 v145, v20, v22, s[44:45]
	v_cndmask_b32_e64 v147, v21, v23, s[44:45]
	s_nop 1
	v_mov_b32_dpp v146, v145 quad_perm:[2,3,0,1] row_mask:0xf bank_mask:0xf
	v_mov_b32_dpp v156, v147 quad_perm:[2,3,0,1] row_mask:0xf bank_mask:0xf
	v_cndmask_b32_e64 v22, v22, v146, s[44:45]
	v_cndmask_b32_e64 v20, v146, v20, s[44:45]
	v_cndmask_b32_e64 v23, v23, v156, s[44:45]
	v_cndmask_b32_e64 v21, v156, v21, s[44:45]
	v_cndmask_b32_e64 v145, v24, v25, s[42:43]
	v_cndmask_b32_e64 v147, v26, v27, s[42:43]
	s_nop 1
	v_mov_b32_dpp v146, v145 quad_perm:[1,0,3,2] row_mask:0xf bank_mask:0xf
	v_mov_b32_dpp v156, v147 quad_perm:[1,0,3,2] row_mask:0xf bank_mask:0xf
	v_cndmask_b32_e64 v25, v25, v146, s[42:43]
	v_cndmask_b32_e64 v24, v146, v24, s[42:43]
	v_cndmask_b32_e64 v27, v27, v156, s[42:43]
	v_cndmask_b32_e64 v26, v156, v26, s[42:43]
	v_cndmask_b32_e64 v145, v24, v26, s[44:45]
	v_cndmask_b32_e64 v147, v25, v27, s[44:45]
	s_nop 1
	v_mov_b32_dpp v146, v145 quad_perm:[2,3,0,1] row_mask:0xf bank_mask:0xf
; #define LAS __attribute__((address_space(3)))
; __device__ __forceinline__ unsigned pk2(float lo, float hi) { const f32x2_t_ v = {lo, hi}; return __builtin_bit_cast(unsigned, __builtin_convertvector(v, bf16x2_t_)); }
; __device__ __forceinline__ void hg_chunk(const LAS unsigned char* sl, f32x4 (&S)[8], float* Orow, int nvalid, int vs, int lane) {
;     const int r = lane & 15, q = lane >> 4;
;     const bf16x8 vfr = *(const LAS bf16x8*)(sl + 16384 + ((vs * 64 + lane) << 4));
;     f32x4 o0 = {0.f, 0.f, 0.f, 0.f}, o1 = {0.f, 0.f, 0.f, 0.f};
;     { const bf16x8 s0 = *(const LAS bf16x8*)(sl + 24576 + (lane << 4)), s1 = *(const LAS bf16x8*)(sl + 24576 + ((64 + lane) << 4));
;       o0 = __builtin_amdgcn_mfma_f32_16x16x32_bf16(s0, vfr, o0, 0, 0, 0); o1 = __builtin_amdgcn_mfma_f32_16x16x32_bf16(s1, vfr, o1, 0, 0, 0); }
; #pragma unroll
;     for (int m = 0; m < 4; ++m) {
;         v4u sw; sw.x = pk2(S[2 * m][0], S[2 * m][1]); sw.y = pk2(S[2 * m][2], S[2 * m][3]); sw.z = pk2(S[2 * m + 1][0], S[2 * m + 1][1]); sw.w = pk2(S[2 * m + 1][2], S[2 * m + 1][3]);
;         const bf16x8 sb = __builtin_bit_cast(bf16x8, sw);
;         const bf16x8 a0 = *(const LAS bf16x8*)(sl + ((m * 64 + lane) << 4)), a1 = *(const LAS bf16x8*)(sl + (((4 + m) * 64 + lane) << 4));
;         o0 = __builtin_amdgcn_mfma_f32_16x16x32_bf16(a0, sb, o0, 0, 0, 0); o1 = __builtin_amdgcn_mfma_f32_16x16x32_bf16(a1, sb, o1, 0, 0, 0);
;     }
; #pragma unroll
;     for (int i = 0; i < 4; ++i) { const int c0 = 4 * q + i;
;         if (c0 < nvalid) Orow[(size_t)c0 * DA + 16 * vs + r] = o0[i];
;         if (c0 + 16 < nvalid) Orow[(size_t)(c0 + 16) * DA + 16 * vs + r] = o1[i]; }
; #pragma unroll
;     for (int kb = 0; kb < 8; ++kb) { const f32x4 d = *(const LAS f32x4*)(sl + 26624 + ((16 * kb + 4 * q) << 2));
;         const bf16x8 ke = *(const LAS bf16x8*)(sl + 8192 + ((kb * 64 + lane) << 4));
;         S[kb] = __builtin_amdgcn_mfma_f32_16x16x32_bf16(ke, vfr, S[kb] * d, 0, 0, 0); }
	v_mov_b32_dpp v156, v147 quad_perm:[2,3,0,1] row_mask:0xf bank_mask:0xf
	v_cndmask_b32_e64 v26, v26, v146, s[44:45]
	v_cndmask_b32_e64 v24, v146, v24, s[44:45]
	v_cndmask_b32_e64 v27, v27, v156, s[44:45]
	v_cndmask_b32_e64 v25, v156, v25, s[44:45]
	v_cndmask_b32_e64 v145, v28, v29, s[42:43]
	v_cndmask_b32_e64 v147, v30, v31, s[42:43]
	s_nop 1
	v_mov_b32_dpp v146, v145 quad_perm:[1,0,3,2] row_mask:0xf bank_mask:0xf
	v_mov_b32_dpp v156, v147 quad_perm:[1,0,3,2] row_mask:0xf bank_mask:0xf
	v_cndmask_b32_e64 v29, v29, v146, s[42:43]
	v_cndmask_b32_e64 v28, v146, v28, s[42:43]
	v_cndmask_b32_e64 v31, v31, v156, s[42:43]
	v_cndmask_b32_e64 v30, v156, v30, s[42:43]
	v_cndmask_b32_e64 v145, v28, v30, s[44:45]
	v_cndmask_b32_e64 v147, v29, v31, s[44:45]
	s_nop 1
	v_mov_b32_dpp v146, v145 quad_perm:[2,3,0,1] row_mask:0xf bank_mask:0xf
	v_mov_b32_dpp v156, v147 quad_perm:[2,3,0,1] row_mask:0xf bank_mask:0xf
	v_cndmask_b32_e64 v30, v30, v146, s[44:45]
	v_cndmask_b32_e64 v28, v146, v28, s[44:45]
	v_cndmask_b32_e64 v31, v31, v156, s[44:45]
	v_cndmask_b32_e64 v29, v156, v29, s[44:45]
	v_cndmask_b32_e64 v145, v32, v33, s[42:43]
	v_cndmask_b32_e64 v147, v34, v35, s[42:43]
	s_nop 1
	v_mov_b32_dpp v146, v145 quad_perm:[1,0,3,2] row_mask:0xf bank_mask:0xf
	v_mov_b32_dpp v156, v147 quad_perm:[1,0,3,2] row_mask:0xf bank_mask:0xf
	v_cndmask_b32_e64 v33, v33, v146, s[42:43]
	v_cndmask_b32_e64 v32, v146, v32, s[42:43]
	v_cndmask_b32_e64 v35, v35, v156, s[42:43]
	v_cndmask_b32_e64 v34, v156, v34, s[42:43]
	v_cndmask_b32_e64 v145, v32, v34, s[44:45]
	v_cndmask_b32_e64 v147, v33, v35, s[44:45]
	s_nop 1
	v_mov_b32_dpp v146, v145 quad_perm:[2,3,0,1] row_mask:0xf bank_mask:0xf
	v_mov_b32_dpp v156, v147 quad_perm:[2,3,0,1] row_mask:0xf bank_mask:0xf
	v_cndmask_b32_e64 v34, v34, v146, s[44:45]
	v_cndmask_b32_e64 v32, v146, v32, s[44:45]
	v_cndmask_b32_e64 v35, v35, v156, s[44:45]
	v_cndmask_b32_e64 v33, v156, v33, s[44:45]
	v_mov_b32_e32 v1, v142
	v_mov_b32_e32 v2, v143
	v_mov_b32_e32 v3, v144
	ds_read_b128 v[164:167], v3 offset:26624
	ds_read_b128 v[168:171], v3 offset:26688
	ds_read_b128 v[172:175], v3 offset:26752
	ds_read_b128 v[176:179], v3 offset:26816
	ds_read_b128 v[180:183], v3 offset:26880
	ds_read_b128 v[184:187], v3 offset:26944
	ds_read_b128 v[148:151], v3 offset:27008
	ds_read_b128 v[152:155], v3 offset:27072
	ds_read_b128 v[84:87], v2 offset:16384
	ds_read_b128 v[88:91], v1 offset:24576
	ds_read_b128 v[92:95], v1 offset:0
	ds_read_b128 v[96:99], v1 offset:1024
	ds_read_b128 v[100:103], v1 offset:2048
	ds_read_b128 v[104:107], v1 offset:3072
	v_cvt_pk_bf16_f32 v68, v4, v5
	v_cvt_pk_bf16_f32 v69, v6, v7
	v_cvt_pk_bf16_f32 v70, v8, v9
	v_cvt_pk_bf16_f32 v71, v10, v11
	v_cvt_pk_bf16_f32 v72, v12, v13
	v_cvt_pk_bf16_f32 v73, v14, v15
	v_cvt_pk_bf16_f32 v74, v16, v17
	v_cvt_pk_bf16_f32 v75, v18, v19
	v_cvt_pk_bf16_f32 v76, v20, v21
	v_cvt_pk_bf16_f32 v77, v22, v23
	v_cvt_pk_bf16_f32 v78, v24, v25
	v_cvt_pk_bf16_f32 v79, v26, v27
	v_cvt_pk_bf16_f32 v80, v28, v29
	v_cvt_pk_bf16_f32 v81, v30, v31
	v_cvt_pk_bf16_f32 v82, v32, v33
	v_cvt_pk_bf16_f32 v83, v34, v35
	s_waitcnt lgkmcnt(6)
	v_pk_mul_f32 v[4:5], v[4:5], v[164:165]
	v_pk_mul_f32 v[6:7], v[6:7], v[166:167]
	v_pk_mul_f32 v[8:9], v[8:9], v[168:169]
	v_pk_mul_f32 v[10:11], v[10:11], v[170:171]
	v_pk_mul_f32 v[12:13], v[12:13], v[172:173]
	v_pk_mul_f32 v[14:15], v[14:15], v[174:175]
	v_pk_mul_f32 v[16:17], v[16:17], v[176:177]
	v_pk_mul_f32 v[18:19], v[18:19], v[178:179]
	v_pk_mul_f32 v[20:21], v[20:21], v[180:181]
	v_pk_mul_f32 v[22:23], v[22:23], v[182:183]
	v_pk_mul_f32 v[24:25], v[24:25], v[184:185]
	v_pk_mul_f32 v[26:27], v[26:27], v[186:187]
	v_pk_mul_f32 v[28:29], v[28:29], v[148:149]
	v_pk_mul_f32 v[30:31], v[30:31], v[150:151]
	v_pk_mul_f32 v[32:33], v[32:33], v[152:153]
	v_pk_mul_f32 v[34:35], v[34:35], v[154:155]
	ds_read_b128 v[108:111], v1 offset:8192
	ds_read_b128 v[112:115], v1 offset:9216
	ds_read_b128 v[116:119], v1 offset:10240
	ds_read_b128 v[120:123], v1 offset:11264
	ds_read_b128 v[124:127], v1 offset:12288
	ds_read_b128 v[128:131], v1 offset:13312
	ds_read_b128 v[132:135], v1 offset:14336
	ds_read_b128 v[136:139], v1 offset:15360
	s_waitcnt lgkmcnt(12)
	v_mfma_f32_16x16x32_bf16 v[196:199], v[88:91], v[84:87], 0
	s_waitcnt lgkmcnt(11)
	v_mfma_f32_16x16x32_bf16 v[196:199], v[92:95], v[68:71], v[196:199]
	s_waitcnt lgkmcnt(10)
	v_mfma_f32_16x16x32_bf16 v[196:199], v[96:99], v[72:75], v[196:199]
	s_waitcnt lgkmcnt(9)
	v_mfma_f32_16x16x32_bf16 v[196:199], v[100:103], v[76:79], v[196:199]
	s_waitcnt lgkmcnt(8)
	v_mfma_f32_16x16x32_bf16 v[196:199], v[104:107], v[80:83], v[196:199]
	s_waitcnt lgkmcnt(7)
	v_mfma_f32_16x16x32_bf16 v[4:7], v[108:111], v[84:87], v[4:7]
	s_waitcnt lgkmcnt(6)
	v_mfma_f32_16x16x32_bf16 v[8:11], v[112:115], v[84:87], v[8:11]
	s_waitcnt lgkmcnt(5)
	v_mfma_f32_16x16x32_bf16 v[12:15], v[116:119], v[84:87], v[12:15]
	s_waitcnt lgkmcnt(4)
	v_mfma_f32_16x16x32_bf16 v[16:19], v[120:123], v[84:87], v[16:19]
	s_waitcnt lgkmcnt(3)
	v_mfma_f32_16x16x32_bf16 v[20:23], v[124:127], v[84:87], v[20:23]
	s_waitcnt lgkmcnt(2)
	v_mfma_f32_16x16x32_bf16 v[24:27], v[128:131], v[84:87], v[24:27]
	s_waitcnt lgkmcnt(1)
	v_mfma_f32_16x16x32_bf16 v[28:31], v[132:135], v[84:87], v[28:31]
	s_waitcnt lgkmcnt(0)
; __device__ __forceinline__ void hg_chunk(const LAS unsigned char* sl, f32x4 (&S)[8], float* Orow, int nvalid, int vs, int lane) {
;     ...
; #pragma unroll
;     for (int i = 0; i < 4; ++i) { const int c0 = 4 * q + i;
;         if (c0 < nvalid) Orow[(size_t)c0 * DA + 16 * vs + r] = o0[i];
;         if (c0 + 16 < nvalid) Orow[(size_t)(c0 + 16) * DA + 16 * vs + r] = o1[i]; }
; __device__ __forceinline__ void hg_seq(const Frame& F, unsigned char* ws, const float* s0, float* sout, float* Og, int seq, bool sample, int vs_base, int nvs) {
;     ...
;     if (active) {
; #pragma unroll
;     for (int kb = 0; kb < 8; ++kb)
; #pragma unroll
;         for (int i = 0; i < 4; ++i) sout[((size_t)seq * 128 + 16 * kb + 4 * q + i) * 128 + 16 * vs + r] = S[kb][i];
	v_mfma_f32_16x16x32_bf16 v[32:35], v[136:139], v[84:87], v[32:35]
	s_mov_b32 exec_hi, 0
	global_store_dword v208, v196, s[12:13]
	global_store_dword v208, v197, s[12:13] offset:2048
	global_store_dword v209, v198, s[12:13]
	global_store_dword v209, v199, s[12:13] offset:2048
	s_mov_b64 exec, -1
	s_add_u32 s12, s12, 0x80000
	s_addc_u32 s13, s13, 0
	s_nop 7
	v_cndmask_b32_e64 v145, v4, v5, s[42:43]
	v_cndmask_b32_e64 v147, v6, v7, s[42:43]
	s_nop 1
	v_mov_b32_dpp v146, v145 quad_perm:[1,0,3,2] row_mask:0xf bank_mask:0xf
	v_mov_b32_dpp v156, v147 quad_perm:[1,0,3,2] row_mask:0xf bank_mask:0xf
	v_cndmask_b32_e64 v5, v5, v146, s[42:43]
	v_cndmask_b32_e64 v4, v146, v4, s[42:43]
	v_cndmask_b32_e64 v7, v7, v156, s[42:43]
	v_cndmask_b32_e64 v6, v156, v6, s[42:43]
	v_cndmask_b32_e64 v145, v4, v6, s[44:45]
	v_cndmask_b32_e64 v147, v5, v7, s[44:45]
	s_nop 1
	v_mov_b32_dpp v146, v145 quad_perm:[2,3,0,1] row_mask:0xf bank_mask:0xf
	v_mov_b32_dpp v156, v147 quad_perm:[2,3,0,1] row_mask:0xf bank_mask:0xf
	v_cndmask_b32_e64 v6, v6, v146, s[44:45]
	v_cndmask_b32_e64 v4, v146, v4, s[44:45]
	v_cndmask_b32_e64 v7, v7, v156, s[44:45]
	v_cndmask_b32_e64 v5, v156, v5, s[44:45]
	v_cndmask_b32_e64 v145, v8, v9, s[42:43]
	v_cndmask_b32_e64 v147, v10, v11, s[42:43]
	s_nop 1
	v_mov_b32_dpp v146, v145 quad_perm:[1,0,3,2] row_mask:0xf bank_mask:0xf
	v_mov_b32_dpp v156, v147 quad_perm:[1,0,3,2] row_mask:0xf bank_mask:0xf
	v_cndmask_b32_e64 v9, v9, v146, s[42:43]
	v_cndmask_b32_e64 v8, v146, v8, s[42:43]
	v_cndmask_b32_e64 v11, v11, v156, s[42:43]
	v_cndmask_b32_e64 v10, v156, v10, s[42:43]
	v_cndmask_b32_e64 v145, v8, v10, s[44:45]
	v_cndmask_b32_e64 v147, v9, v11, s[44:45]
	s_nop 1
	v_mov_b32_dpp v146, v145 quad_perm:[2,3,0,1] row_mask:0xf bank_mask:0xf
	v_mov_b32_dpp v156, v147 quad_perm:[2,3,0,1] row_mask:0xf bank_mask:0xf
	v_cndmask_b32_e64 v10, v10, v146, s[44:45]
	v_cndmask_b32_e64 v8, v146, v8, s[44:45]
	v_cndmask_b32_e64 v11, v11, v156, s[44:45]
	v_cndmask_b32_e64 v9, v156, v9, s[44:45]
	v_cndmask_b32_e64 v145, v12, v13, s[42:43]
	v_cndmask_b32_e64 v147, v14, v15, s[42:43]
	s_nop 1
	v_mov_b32_dpp v146, v145 quad_perm:[1,0,3,2] row_mask:0xf bank_mask:0xf
	v_mov_b32_dpp v156, v147 quad_perm:[1,0,3,2] row_mask:0xf bank_mask:0xf
	v_cndmask_b32_e64 v13, v13, v146, s[42:43]
	v_cndmask_b32_e64 v12, v146, v12, s[42:43]
	v_cndmask_b32_e64 v15, v15, v156, s[42:43]
	v_cndmask_b32_e64 v14, v156, v14, s[42:43]
	v_cndmask_b32_e64 v145, v12, v14, s[44:45]
	v_cndmask_b32_e64 v147, v13, v15, s[44:45]
	s_nop 1
	v_mov_b32_dpp v146, v145 quad_perm:[2,3,0,1] row_mask:0xf bank_mask:0xf
	v_mov_b32_dpp v156, v147 quad_perm:[2,3,0,1] row_mask:0xf bank_mask:0xf
	v_cndmask_b32_e64 v14, v14, v146, s[44:45]
	v_cndmask_b32_e64 v12, v146, v12, s[44:45]
	v_cndmask_b32_e64 v15, v15, v156, s[44:45]
	v_cndmask_b32_e64 v13, v156, v13, s[44:45]
	v_cndmask_b32_e64 v145, v16, v17, s[42:43]
	v_cndmask_b32_e64 v147, v18, v19, s[42:43]
	s_nop 1
	v_mov_b32_dpp v146, v145 quad_perm:[1,0,3,2] row_mask:0xf bank_mask:0xf
	v_mov_b32_dpp v156, v147 quad_perm:[1,0,3,2] row_mask:0xf bank_mask:0xf
	v_cndmask_b32_e64 v17, v17, v146, s[42:43]
	v_cndmask_b32_e64 v16, v146, v16, s[42:43]
	v_cndmask_b32_e64 v19, v19, v156, s[42:43]
	v_cndmask_b32_e64 v18, v156, v18, s[42:43]
	v_cndmask_b32_e64 v145, v16, v18, s[44:45]
	v_cndmask_b32_e64 v147, v17, v19, s[44:45]
	s_nop 1
	v_mov_b32_dpp v146, v145 quad_perm:[2,3,0,1] row_mask:0xf bank_mask:0xf
	v_mov_b32_dpp v156, v147 quad_perm:[2,3,0,1] row_mask:0xf bank_mask:0xf
	v_cndmask_b32_e64 v18, v18, v146, s[44:45]
	v_cndmask_b32_e64 v16, v146, v16, s[44:45]
	v_cndmask_b32_e64 v19, v19, v156, s[44:45]
	v_cndmask_b32_e64 v17, v156, v17, s[44:45]
	v_cndmask_b32_e64 v145, v20, v21, s[42:43]
	v_cndmask_b32_e64 v147, v22, v23, s[42:43]
; __device__ __forceinline__ void hg_seq(const Frame& F, unsigned char* ws, const float* s0, float* sout, float* Og, int seq, bool sample, int vs_base, int nvs) {
;     ...
;     if (active) {
; #pragma unroll
;     for (int kb = 0; kb < 8; ++kb)
; #pragma unroll
;         for (int i = 0; i < 4; ++i) sout[((size_t)seq * 128 + 16 * kb + 4 * q + i) * 128 + 16 * vs + r] = S[kb][i];
;     }
	s_nop 1
	v_mov_b32_dpp v146, v145 quad_perm:[1,0,3,2] row_mask:0xf bank_mask:0xf
	v_mov_b32_dpp v156, v147 quad_perm:[1,0,3,2] row_mask:0xf bank_mask:0xf
	v_cndmask_b32_e64 v21, v21, v146, s[42:43]
	v_cndmask_b32_e64 v20, v146, v20, s[42:43]
	v_cndmask_b32_e64 v23, v23, v156, s[42:43]
	v_cndmask_b32_e64 v22, v156, v22, s[42:43]
	v_cndmask_b32_e64 v145, v20, v22, s[44:45]
	v_cndmask_b32_e64 v147, v21, v23, s[44:45]
	s_nop 1
	v_mov_b32_dpp v146, v145 quad_perm:[2,3,0,1] row_mask:0xf bank_mask:0xf
	v_mov_b32_dpp v156, v147 quad_perm:[2,3,0,1] row_mask:0xf bank_mask:0xf
	v_cndmask_b32_e64 v22, v22, v146, s[44:45]
	v_cndmask_b32_e64 v20, v146, v20, s[44:45]
	v_cndmask_b32_e64 v23, v23, v156, s[44:45]
	v_cndmask_b32_e64 v21, v156, v21, s[44:45]
	v_cndmask_b32_e64 v145, v24, v25, s[42:43]
	v_cndmask_b32_e64 v147, v26, v27, s[42:43]
	s_nop 1
	v_mov_b32_dpp v146, v145 quad_perm:[1,0,3,2] row_mask:0xf bank_mask:0xf
	v_mov_b32_dpp v156, v147 quad_perm:[1,0,3,2] row_mask:0xf bank_mask:0xf
	v_cndmask_b32_e64 v25, v25, v146, s[42:43]
	v_cndmask_b32_e64 v24, v146, v24, s[42:43]
	v_cndmask_b32_e64 v27, v27, v156, s[42:43]
	v_cndmask_b32_e64 v26, v156, v26, s[42:43]
	v_cndmask_b32_e64 v145, v24, v26, s[44:45]
	v_cndmask_b32_e64 v147, v25, v27, s[44:45]
	s_nop 1
	v_mov_b32_dpp v146, v145 quad_perm:[2,3,0,1] row_mask:0xf bank_mask:0xf
	v_mov_b32_dpp v156, v147 quad_perm:[2,3,0,1] row_mask:0xf bank_mask:0xf
	v_cndmask_b32_e64 v26, v26, v146, s[44:45]
	v_cndmask_b32_e64 v24, v146, v24, s[44:45]
	v_cndmask_b32_e64 v27, v27, v156, s[44:45]
	v_cndmask_b32_e64 v25, v156, v25, s[44:45]
	v_cndmask_b32_e64 v145, v28, v29, s[42:43]
	v_cndmask_b32_e64 v147, v30, v31, s[42:43]
	s_nop 1
	v_mov_b32_dpp v146, v145 quad_perm:[1,0,3,2] row_mask:0xf bank_mask:0xf
	v_mov_b32_dpp v156, v147 quad_perm:[1,0,3,2] row_mask:0xf bank_mask:0xf
	v_cndmask_b32_e64 v29, v29, v146, s[42:43]
	v_cndmask_b32_e64 v28, v146, v28, s[42:43]
	v_cndmask_b32_e64 v31, v31, v156, s[42:43]
	v_cndmask_b32_e64 v30, v156, v30, s[42:43]
	v_cndmask_b32_e64 v145, v28, v30, s[44:45]
	v_cndmask_b32_e64 v147, v29, v31, s[44:45]
	s_nop 1
	v_mov_b32_dpp v146, v145 quad_perm:[2,3,0,1] row_mask:0xf bank_mask:0xf
	v_mov_b32_dpp v156, v147 quad_perm:[2,3,0,1] row_mask:0xf bank_mask:0xf
	v_cndmask_b32_e64 v30, v30, v146, s[44:45]
	v_cndmask_b32_e64 v28, v146, v28, s[44:45]
	v_cndmask_b32_e64 v31, v31, v156, s[44:45]
	v_cndmask_b32_e64 v29, v156, v29, s[44:45]
	v_cndmask_b32_e64 v145, v32, v33, s[42:43]
	v_cndmask_b32_e64 v147, v34, v35, s[42:43]
	s_nop 1
	v_mov_b32_dpp v146, v145 quad_perm:[1,0,3,2] row_mask:0xf bank_mask:0xf
	v_mov_b32_dpp v156, v147 quad_perm:[1,0,3,2] row_mask:0xf bank_mask:0xf
	v_cndmask_b32_e64 v33, v33, v146, s[42:43]
	v_cndmask_b32_e64 v32, v146, v32, s[42:43]
	v_cndmask_b32_e64 v35, v35, v156, s[42:43]
	v_cndmask_b32_e64 v34, v156, v34, s[42:43]
	v_cndmask_b32_e64 v145, v32, v34, s[44:45]
	v_cndmask_b32_e64 v147, v33, v35, s[44:45]
	s_nop 1
	v_mov_b32_dpp v146, v145 quad_perm:[2,3,0,1] row_mask:0xf bank_mask:0xf
	v_mov_b32_dpp v156, v147 quad_perm:[2,3,0,1] row_mask:0xf bank_mask:0xf
	v_cndmask_b32_e64 v34, v34, v146, s[44:45]
	v_cndmask_b32_e64 v32, v146, v32, s[44:45]
	v_cndmask_b32_e64 v35, v35, v156, s[44:45]
	v_cndmask_b32_e64 v33, v156, v33, s[44:45]
	global_store_dwordx4 v200, v[4:7], s[10:11]
	global_store_dwordx4 v201, v[8:11], s[10:11]
	global_store_dwordx4 v202, v[12:15], s[10:11]
	global_store_dwordx4 v203, v[16:19], s[10:11]
	global_store_dwordx4 v204, v[20:23], s[10:11]
	global_store_dwordx4 v205, v[24:27], s[10:11]
	global_store_dwordx4 v206, v[28:31], s[10:11]
	global_store_dwordx4 v207, v[32:35], s[10:11]
	s_add_u32 s10, s10, s34
	s_addc_u32 s11, s11, 0
	s_waitcnt lgkmcnt(0)
	s_barrier
	s_branch .LBB0_1245

; #define LAS __attribute__((address_space(3)))
; #define LDSBAR() do { asm volatile("s_waitcnt lgkmcnt(0)" ::: "memory"); __builtin_amdgcn_s_barrier(); asm volatile("" ::: "memory"); } while (0)
; __device__ __forceinline__ void hg_seq(const Frame& F, unsigned char* ws, const float* s0, float* sout, float* Og, int seq, bool sample, int vs_base, int nvs) {
;     LAS unsigned char* ring = F.lds;
;     const int tid = F.tid, lane = F.lane, vs = vs_base + F.wave, r = lane & 15, q = lane >> 4;
;     const bool active = F.wave < nvs, vload = (unsigned)((tid >> 6) - vs_base) < (unsigned)nvs;
;     int nch, nvalid, t0, h; const unsigned char *qf, *vf, *lf; int qp, lp; size_t qstep, lstep;
;     if (!sample) { const int b = seq >> 2; h = seq & 3; t0 = b * 2048; nch = 64; nvalid = 32; const size_t e0 = (size_t)t0 * DA + h * 128;
;         qf = ws + WS_Q + e0 * 2; vf = ws + WS_V + e0 * 2; lf = ws + WS_LOGF + e0 * 4; qp = 1024; lp = 2048; qstep = 32 * 1024; lstep = 32 * 2048; }
;     else { const int b = seq >> 2; h = seq & 3; t0 = TP + b * 8; nch = 1; nvalid = 8; const unsigned char* base = (const unsigned char*)sout + (size_t)seq * 65536;
;         qf = base; vf = base + 8192; lf = base + 16384; qp = 256; lp = 512; qstep = 0; lstep = 0; }
;     const size_t offq = (size_t)(tid >> 4) * qp + (tid & 15) * 16, offl0 = (size_t)(tid >> 5) * lp + (tid & 31) * 16, offl1 = (size_t)(16 + (tid >> 5)) * lp + (tid & 31) * 16, offl1c = tid < 160 ? offl1 : offl0;
;     {
;     f32x4 S[8];
;     if (sample && active) {
; #pragma unroll
;         for (int kb = 0; kb < 8; ++kb)
; #pragma unroll
;             for (int i = 0; i < 4; ++i) S[kb][i] = s0[((size_t)seq * 128 + 16 * kb + 4 * q + i) * 128 + 16 * vs + r];
;     } else {
; #pragma unroll
;         for (int kb = 0; kb < 8; ++kb) S[kb] = (f32x4){0.f, 0.f, 0.f, 0.f};
;     }
;     float* Ob = Og + (size_t)t0 * DA + h * 128;
;     ...
;     HgPre R0, R1, R2, R3, R4, R5;
;     R0.l1 = R0.v = (v4u){0u, 0u, 0u, 0u}; R1.l1 = R1.v = (v4u){0u, 0u, 0u, 0u}; R2.l1 = R2.v = (v4u){0u, 0u, 0u, 0u}; R3.l1 = R3.v = (v4u){0u, 0u, 0u, 0u}; R4.l1 = R4.v = (v4u){0u, 0u, 0u, 0u}; R5.l1 = R5.v = (v4u){0u, 0u, 0u, 0u};
;     HG_LOAD(R0, 0); HG_LOAD(R1, 1); HG_LOAD(R2, 2); HG_LOAD(R3, 3); HG_LOAD(R4, 4);
;     HG_STORE(R0, 0); LDSBAR();
.LBB0_1163:
	s_or_b64 exec, exec, s[16:17]
	s_load_dwordx2 s[16:17], s[0:1], 0x10
	s_sub_i32 s46, s2, 0x80
	s_mov_b64 exec, -1
	s_waitcnt lgkmcnt(0)
	s_lshl_b32 s3, s46, 16
	s_add_u32 s8, s16, s3
	s_addc_u32 s9, s17, 0
	s_add_u32 s10, s20, 0x4608000
	s_addc_u32 s11, s21, 0
	s_add_u32 s10, s10, s3
	s_addc_u32 s11, s11, 0
	s_lshr_b32 s6, s46, 2
	s_lshl_b32 s6, s6, 14
	s_and_b32 s7, s46, 3
	s_lshl_b32 s7, s7, 9
	s_add_i32 s6, s6, s7
	s_add_u32 s12, s22, 0x4080000
	s_addc_u32 s13, s23, 0
	s_add_u32 s12, s12, s6
	s_addc_u32 s13, s13, 0
	s_add_u32 s8, s8, 0x800000
	s_addc_u32 s9, s9, 0
	s_add_u32 s10, s10, 0x800000
	s_addc_u32 s11, s11, 0
	s_add_u32 s12, s12, 0x80000
	s_addc_u32 s13, s13, 0
	s_mov_b32 s34, 0x800000
	s_mov_b32 s35, 0
	v_lshlrev_b32_e32 v142, 4, v189
	s_lshl_b32 s3, s50, 10
	v_add_u32_e32 v143, s3, v142
	v_lshrrev_b32_e32 v1, 4, v189
	v_lshlrev_b32_e32 v144, 4, v1
	s_lshl_b32 s3, s50, 4
	v_and_b32_e32 v2, 15, v189
	v_add_u32_e32 v2, s3, v2
	v_lshlrev_b32_e32 v2, 2, v2
	v_lshl_add_u32 v208, v1, 13, v2
	v_add_u32_e32 v209, 0x1000, v208
	v_and_b32_e32 v3, 3, v189
	v_lshlrev_b32_e32 v3, 9, v3
	v_lshl_add_u32 v3, v1, 11, v3
	v_bfe_u32 v200, v189, 2, 2
	v_lshl_add_u32 v3, v200, 4, v3
	s_lshl_b32 s3, s50, 6
	v_add_u32_e32 v200, s3, v3
	v_add_u32_e32 v201, 0x2000, v200
	v_add_u32_e32 v202, 0x4000, v200
	v_add_u32_e32 v203, 0x6000, v200
	v_add_u32_e32 v204, 0x8000, v200
	v_add_u32_e32 v205, 0xa000, v200
	v_add_u32_e32 v206, 0xc000, v200
	v_add_u32_e32 v207, 0xe000, v200
	s_mov_b32 s42, 0x55555555
	s_mov_b32 s43, 0x55555555
	s_mov_b32 s44, 0x33333333
	s_mov_b32 s45, 0x33333333
	v_mov_b32_e32 v3, 0
	v_mov_b32_e32 v2, v143
	v_lshl_add_u64 v[210:211], s[10:11], 0, v[2:3]
	s_add_u32 s6, s10, 0x2000
	s_addc_u32 s7, s11, 0
	v_lshl_add_u64 v[212:213], s[6:7], 0, v[2:3]
	s_add_u32 s6, s10, 0x4000
	s_addc_u32 s7, s11, 0
	v_lshl_add_u64 v[214:215], s[6:7], 0, v[2:3]
	s_mov_b32 s36, 0
	s_lshl_b32 s37, s50, 10
	s_cmp_lt_u32 s50, 3
	s_cbranch_scc0 .Lsmpb_p4_done
	s_movk_i32 s36, 0x6000
	s_add_i32 s37, s37, 0x6000
.Lsmpb_p4_done:
	s_add_u32 s6, s10, s36
	s_addc_u32 s7, s11, 0
	v_lshl_add_u64 v[140:141], s[6:7], 0, v[2:3]
	s_lshl_b32 s38, s50, 10
	s_add_i32 s39, s38, 0x4000
	s_add_i32 s40, s38, 0x2000
	s_mov_b32 m0, s38
	s_nop 0
	global_load_lds_dwordx4 v[210:211], off
	s_mov_b32 m0, s39
	s_nop 0
	global_load_lds_dwordx4 v[212:213], off
	s_mov_b32 m0, s40
	s_nop 0
	global_load_lds_dwordx4 v[214:215], off
	s_mov_b32 m0, s37
	s_nop 0
	global_load_lds_dwordx4 v[140:141], off
	v_lshl_add_u64 v[210:211], v[210:211], 0, s[34:35]
	v_lshl_add_u64 v[212:213], v[212:213], 0, s[34:35]
	v_lshl_add_u64 v[214:215], v[214:215], 0, s[34:35]
	v_lshl_add_u64 v[140:141], v[140:141], 0, s[34:35]
	s_add_i32 m0, s38, 0x6c00
	s_nop 0
	global_load_lds_dwordx4 v[210:211], off
	s_add_i32 m0, s39, 0x6c00
	s_nop 0
	global_load_lds_dwordx4 v[212:213], off
	s_add_i32 m0, s40, 0x6c00
	s_nop 0
	global_load_lds_dwordx4 v[214:215], off
	s_add_i32 m0, s37, 0x6c00
	s_nop 0
	global_load_lds_dwordx4 v[140:141], off
	v_lshl_add_u64 v[210:211], v[210:211], 0, s[34:35]
	v_lshl_add_u64 v[212:213], v[212:213], 0, s[34:35]
	v_lshl_add_u64 v[214:215], v[214:215], 0, s[34:35]
	v_lshl_add_u64 v[140:141], v[140:141], 0, s[34:35]
	s_add_i32 m0, s38, 0xd800
	s_nop 0
	global_load_lds_dwordx4 v[210:211], off
	s_add_i32 m0, s39, 0xd800
	s_nop 0
	global_load_lds_dwordx4 v[212:213], off
	s_add_i32 m0, s40, 0xd800
	s_nop 0
	global_load_lds_dwordx4 v[214:215], off
	s_add_i32 m0, s37, 0xd800
	s_nop 0
	global_load_lds_dwordx4 v[140:141], off
	global_load_dwordx4 v[4:7], v200, s[8:9]
	global_load_dwordx4 v[8:11], v201, s[8:9]
	global_load_dwordx4 v[12:15], v202, s[8:9]
	global_load_dwordx4 v[16:19], v203, s[8:9]
	global_load_dwordx4 v[20:23], v204, s[8:9]
	global_load_dwordx4 v[24:27], v205, s[8:9]
	global_load_dwordx4 v[28:31], v206, s[8:9]
	global_load_dwordx4 v[32:35], v207, s[8:9]
	s_add_u32 s8, s8, s34
	s_addc_u32 s9, s9, 0
	global_load_dwordx4 v[36:39], v200, s[8:9]
	global_load_dwordx4 v[40:43], v201, s[8:9]
	global_load_dwordx4 v[44:47], v202, s[8:9]
	global_load_dwordx4 v[48:51], v203, s[8:9]
	global_load_dwordx4 v[52:55], v204, s[8:9]
	global_load_dwordx4 v[56:59], v205, s[8:9]
	global_load_dwordx4 v[60:63], v206, s[8:9]
	global_load_dwordx4 v[64:67], v207, s[8:9]
	s_add_u32 s8, s8, s34
	s_addc_u32 s9, s9, 0
	s_waitcnt vmcnt(8)
	s_barrier
; __device__ __forceinline__ void hg_seq(const Frame& F, unsigned char* ws, const float* s0, float* sout, float* Og, int seq, bool sample, int vs_base, int nvs) {
;     ...
;     if (sample && active) {
; #pragma unroll
;         for (int kb = 0; kb < 8; ++kb)
; #pragma unroll
;             for (int i = 0; i < 4; ++i) S[kb][i] = s0[((size_t)seq * 128 + 16 * kb + 4 * q + i) * 128 + 16 * vs + r];
	v_cndmask_b32_e64 v145, v4, v5, s[42:43]
	v_cndmask_b32_e64 v147, v6, v7, s[42:43]
	s_nop 1
	v_mov_b32_dpp v146, v145 quad_perm:[1,0,3,2] row_mask:0xf bank_mask:0xf
	v_mov_b32_dpp v156, v147 quad_perm:[1,0,3,2] row_mask:0xf bank_mask:0xf
	v_cndmask_b32_e64 v5, v5, v146, s[42:43]
	v_cndmask_b32_e64 v4, v146, v4, s[42:43]
	v_cndmask_b32_e64 v7, v7, v156, s[42:43]
	v_cndmask_b32_e64 v6, v156, v6, s[42:43]
	v_cndmask_b32_e64 v145, v4, v6, s[44:45]
	v_cndmask_b32_e64 v147, v5, v7, s[44:45]
	s_nop 1
	v_mov_b32_dpp v146, v145 quad_perm:[2,3,0,1] row_mask:0xf bank_mask:0xf
	v_mov_b32_dpp v156, v147 quad_perm:[2,3,0,1] row_mask:0xf bank_mask:0xf
	v_cndmask_b32_e64 v6, v6, v146, s[44:45]
	v_cndmask_b32_e64 v4, v146, v4, s[44:45]
	v_cndmask_b32_e64 v7, v7, v156, s[44:45]
	v_cndmask_b32_e64 v5, v156, v5, s[44:45]
	v_cndmask_b32_e64 v145, v8, v9, s[42:43]
	v_cndmask_b32_e64 v147, v10, v11, s[42:43]
	s_nop 1
	v_mov_b32_dpp v146, v145 quad_perm:[1,0,3,2] row_mask:0xf bank_mask:0xf
	v_mov_b32_dpp v156, v147 quad_perm:[1,0,3,2] row_mask:0xf bank_mask:0xf
	v_cndmask_b32_e64 v9, v9, v146, s[42:43]
	v_cndmask_b32_e64 v8, v146, v8, s[42:43]
	v_cndmask_b32_e64 v11, v11, v156, s[42:43]
	v_cndmask_b32_e64 v10, v156, v10, s[42:43]
	v_cndmask_b32_e64 v145, v8, v10, s[44:45]
	v_cndmask_b32_e64 v147, v9, v11, s[44:45]
	s_nop 1
	v_mov_b32_dpp v146, v145 quad_perm:[2,3,0,1] row_mask:0xf bank_mask:0xf
	v_mov_b32_dpp v156, v147 quad_perm:[2,3,0,1] row_mask:0xf bank_mask:0xf
	v_cndmask_b32_e64 v10, v10, v146, s[44:45]
	v_cndmask_b32_e64 v8, v146, v8, s[44:45]
	v_cndmask_b32_e64 v11, v11, v156, s[44:45]
	v_cndmask_b32_e64 v9, v156, v9, s[44:45]
	v_cndmask_b32_e64 v145, v12, v13, s[42:43]
	v_cndmask_b32_e64 v147, v14, v15, s[42:43]
	s_nop 1
	v_mov_b32_dpp v146, v145 quad_perm:[1,0,3,2] row_mask:0xf bank_mask:0xf
	v_mov_b32_dpp v156, v147 quad_perm:[1,0,3,2] row_mask:0xf bank_mask:0xf
	v_cndmask_b32_e64 v13, v13, v146, s[42:43]
	v_cndmask_b32_e64 v12, v146, v12, s[42:43]
	v_cndmask_b32_e64 v15, v15, v156, s[42:43]
	v_cndmask_b32_e64 v14, v156, v14, s[42:43]
	v_cndmask_b32_e64 v145, v12, v14, s[44:45]
	v_cndmask_b32_e64 v147, v13, v15, s[44:45]
	s_nop 1
	v_mov_b32_dpp v146, v145 quad_perm:[2,3,0,1] row_mask:0xf bank_mask:0xf
	v_mov_b32_dpp v156, v147 quad_perm:[2,3,0,1] row_mask:0xf bank_mask:0xf
	v_cndmask_b32_e64 v14, v14, v146, s[44:45]
	v_cndmask_b32_e64 v12, v146, v12, s[44:45]
	v_cndmask_b32_e64 v15, v15, v156, s[44:45]
	v_cndmask_b32_e64 v13, v156, v13, s[44:45]
	v_cndmask_b32_e64 v145, v16, v17, s[42:43]
	v_cndmask_b32_e64 v147, v18, v19, s[42:43]
	s_nop 1
	v_mov_b32_dpp v146, v145 quad_perm:[1,0,3,2] row_mask:0xf bank_mask:0xf
	v_mov_b32_dpp v156, v147 quad_perm:[1,0,3,2] row_mask:0xf bank_mask:0xf
	v_cndmask_b32_e64 v17, v17, v146, s[42:43]
	v_cndmask_b32_e64 v16, v146, v16, s[42:43]
	v_cndmask_b32_e64 v19, v19, v156, s[42:43]
	v_cndmask_b32_e64 v18, v156, v18, s[42:43]
	v_cndmask_b32_e64 v145, v16, v18, s[44:45]
	v_cndmask_b32_e64 v147, v17, v19, s[44:45]
	s_nop 1
	v_mov_b32_dpp v146, v145 quad_perm:[2,3,0,1] row_mask:0xf bank_mask:0xf
	v_mov_b32_dpp v156, v147 quad_perm:[2,3,0,1] row_mask:0xf bank_mask:0xf
	v_cndmask_b32_e64 v18, v18, v146, s[44:45]
	v_cndmask_b32_e64 v16, v146, v16, s[44:45]
	v_cndmask_b32_e64 v19, v19, v156, s[44:45]
	v_cndmask_b32_e64 v17, v156, v17, s[44:45]
	v_cndmask_b32_e64 v145, v20, v21, s[42:43]
	v_cndmask_b32_e64 v147, v22, v23, s[42:43]
	s_nop 1
	v_mov_b32_dpp v146, v145 quad_perm:[1,0,3,2] row_mask:0xf bank_mask:0xf
	v_mov_b32_dpp v156, v147 quad_perm:[1,0,3,2] row_mask:0xf bank_mask:0xf
	v_cndmask_b32_e64 v21, v21, v146, s[42:43]
	v_cndmask_b32_e64 v20, v146, v20, s[42:43]
	v_cndmask_b32_e64 v23, v23, v156, s[42:43]
	v_cndmask_b32_e64 v22, v156, v22, s[42:43]
	v_cndmask_b32_e64 v145, v20, v22, s[44:45]
	v_cndmask_b32_e64 v147, v21, v23, s[44:45]
	s_nop 1
	v_mov_b32_dpp v146, v145 quad_perm:[2,3,0,1] row_mask:0xf bank_mask:0xf
	v_mov_b32_dpp v156, v147 quad_perm:[2,3,0,1] row_mask:0xf bank_mask:0xf
	v_cndmask_b32_e64 v22, v22, v146, s[44:45]
	v_cndmask_b32_e64 v20, v146, v20, s[44:45]
	v_cndmask_b32_e64 v23, v23, v156, s[44:45]
	v_cndmask_b32_e64 v21, v156, v21, s[44:45]
	v_cndmask_b32_e64 v145, v24, v25, s[42:43]
	v_cndmask_b32_e64 v147, v26, v27, s[42:43]
	s_nop 1
	v_mov_b32_dpp v146, v145 quad_perm:[1,0,3,2] row_mask:0xf bank_mask:0xf
	v_mov_b32_dpp v156, v147 quad_perm:[1,0,3,2] row_mask:0xf bank_mask:0xf
	v_cndmask_b32_e64 v25, v25, v146, s[42:43]
	v_cndmask_b32_e64 v24, v146, v24, s[42:43]
	v_cndmask_b32_e64 v27, v27, v156, s[42:43]
	v_cndmask_b32_e64 v26, v156, v26, s[42:43]
	v_cndmask_b32_e64 v145, v24, v26, s[44:45]
	v_cndmask_b32_e64 v147, v25, v27, s[44:45]
	s_nop 1
	v_mov_b32_dpp v146, v145 quad_perm:[2,3,0,1] row_mask:0xf bank_mask:0xf
	v_mov_b32_dpp v156, v147 quad_perm:[2,3,0,1] row_mask:0xf bank_mask:0xf
	v_cndmask_b32_e64 v26, v26, v146, s[44:45]
	v_cndmask_b32_e64 v24, v146, v24, s[44:45]
	v_cndmask_b32_e64 v27, v27, v156, s[44:45]
	v_cndmask_b32_e64 v25, v156, v25, s[44:45]
	v_cndmask_b32_e64 v145, v28, v29, s[42:43]
	v_cndmask_b32_e64 v147, v30, v31, s[42:43]
	s_nop 1
	v_mov_b32_dpp v146, v145 quad_perm:[1,0,3,2] row_mask:0xf bank_mask:0xf
	v_mov_b32_dpp v156, v147 quad_perm:[1,0,3,2] row_mask:0xf bank_mask:0xf
	v_cndmask_b32_e64 v29, v29, v146, s[42:43]
	v_cndmask_b32_e64 v28, v146, v28, s[42:43]
	v_cndmask_b32_e64 v31, v31, v156, s[42:43]
	v_cndmask_b32_e64 v30, v156, v30, s[42:43]
	v_cndmask_b32_e64 v145, v28, v30, s[44:45]
	v_cndmask_b32_e64 v147, v29, v31, s[44:45]
	s_nop 1
	v_mov_b32_dpp v146, v145 quad_perm:[2,3,0,1] row_mask:0xf bank_mask:0xf
	v_mov_b32_dpp v156, v147 quad_perm:[2,3,0,1] row_mask:0xf bank_mask:0xf
; #define LAS __attribute__((address_space(3)))
; __device__ __forceinline__ unsigned pk2(float lo, float hi) { const f32x2_t_ v = {lo, hi}; return __builtin_bit_cast(unsigned, __builtin_convertvector(v, bf16x2_t_)); }
; __device__ __forceinline__ void hg_chunk(const LAS unsigned char* sl, f32x4 (&S)[8], float* Orow, int nvalid, int vs, int lane) {
;     const int r = lane & 15, q = lane >> 4;
;     const bf16x8 vfr = *(const LAS bf16x8*)(sl + 16384 + ((vs * 64 + lane) << 4));
;     f32x4 o0 = {0.f, 0.f, 0.f, 0.f}, o1 = {0.f, 0.f, 0.f, 0.f};
;     { const bf16x8 s0 = *(const LAS bf16x8*)(sl + 24576 + (lane << 4)), s1 = *(const LAS bf16x8*)(sl + 24576 + ((64 + lane) << 4));
;       o0 = __builtin_amdgcn_mfma_f32_16x16x32_bf16(s0, vfr, o0, 0, 0, 0); o1 = __builtin_amdgcn_mfma_f32_16x16x32_bf16(s1, vfr, o1, 0, 0, 0); }
; #pragma unroll
;     for (int m = 0; m < 4; ++m) {
;         v4u sw; sw.x = pk2(S[2 * m][0], S[2 * m][1]); sw.y = pk2(S[2 * m][2], S[2 * m][3]); sw.z = pk2(S[2 * m + 1][0], S[2 * m + 1][1]); sw.w = pk2(S[2 * m + 1][2], S[2 * m + 1][3]);
;         const bf16x8 sb = __builtin_bit_cast(bf16x8, sw);
;         const bf16x8 a0 = *(const LAS bf16x8*)(sl + ((m * 64 + lane) << 4)), a1 = *(const LAS bf16x8*)(sl + (((4 + m) * 64 + lane) << 4));
;         o0 = __builtin_amdgcn_mfma_f32_16x16x32_bf16(a0, sb, o0, 0, 0, 0); o1 = __builtin_amdgcn_mfma_f32_16x16x32_bf16(a1, sb, o1, 0, 0, 0);
;     }
; #pragma unroll
;     for (int i = 0; i < 4; ++i) { const int c0 = 4 * q + i;
;         if (c0 < nvalid) Orow[(size_t)c0 * DA + 16 * vs + r] = o0[i];
;         if (c0 + 16 < nvalid) Orow[(size_t)(c0 + 16) * DA + 16 * vs + r] = o1[i]; }
; #pragma unroll
;     for (int kb = 0; kb < 8; ++kb) { const f32x4 d = *(const LAS f32x4*)(sl + 26624 + ((16 * kb + 4 * q) << 2));
;         const bf16x8 ke = *(const LAS bf16x8*)(sl + 8192 + ((kb * 64 + lane) << 4));
;         S[kb] = __builtin_amdgcn_mfma_f32_16x16x32_bf16(ke, vfr, S[kb] * d, 0, 0, 0); }
	v_cndmask_b32_e64 v30, v30, v146, s[44:45]
	v_cndmask_b32_e64 v28, v146, v28, s[44:45]
	v_cndmask_b32_e64 v31, v31, v156, s[44:45]
	v_cndmask_b32_e64 v29, v156, v29, s[44:45]
	v_cndmask_b32_e64 v145, v32, v33, s[42:43]
	v_cndmask_b32_e64 v147, v34, v35, s[42:43]
	s_nop 1
	v_mov_b32_dpp v146, v145 quad_perm:[1,0,3,2] row_mask:0xf bank_mask:0xf
	v_mov_b32_dpp v156, v147 quad_perm:[1,0,3,2] row_mask:0xf bank_mask:0xf
	v_cndmask_b32_e64 v33, v33, v146, s[42:43]
	v_cndmask_b32_e64 v32, v146, v32, s[42:43]
	v_cndmask_b32_e64 v35, v35, v156, s[42:43]
	v_cndmask_b32_e64 v34, v156, v34, s[42:43]
	v_cndmask_b32_e64 v145, v32, v34, s[44:45]
	v_cndmask_b32_e64 v147, v33, v35, s[44:45]
	s_nop 1
	v_mov_b32_dpp v146, v145 quad_perm:[2,3,0,1] row_mask:0xf bank_mask:0xf
	v_mov_b32_dpp v156, v147 quad_perm:[2,3,0,1] row_mask:0xf bank_mask:0xf
	v_cndmask_b32_e64 v34, v34, v146, s[44:45]
	v_cndmask_b32_e64 v32, v146, v32, s[44:45]
	v_cndmask_b32_e64 v35, v35, v156, s[44:45]
	v_cndmask_b32_e64 v33, v156, v33, s[44:45]
	v_mov_b32_e32 v1, v142
	v_mov_b32_e32 v2, v143
	v_mov_b32_e32 v3, v144
	ds_read_b128 v[164:167], v3 offset:26624
	ds_read_b128 v[168:171], v3 offset:26688
	ds_read_b128 v[172:175], v3 offset:26752
	ds_read_b128 v[176:179], v3 offset:26816
	ds_read_b128 v[180:183], v3 offset:26880
	ds_read_b128 v[184:187], v3 offset:26944
	ds_read_b128 v[148:151], v3 offset:27008
	ds_read_b128 v[152:155], v3 offset:27072
	ds_read_b128 v[84:87], v2 offset:16384
	ds_read_b128 v[88:91], v1 offset:24576
	ds_read_b128 v[92:95], v1 offset:0
	ds_read_b128 v[96:99], v1 offset:1024
	ds_read_b128 v[100:103], v1 offset:2048
	ds_read_b128 v[104:107], v1 offset:3072
	v_cvt_pk_bf16_f32 v68, v4, v5
	v_cvt_pk_bf16_f32 v69, v6, v7
	v_cvt_pk_bf16_f32 v70, v8, v9
	v_cvt_pk_bf16_f32 v71, v10, v11
	v_cvt_pk_bf16_f32 v72, v12, v13
	v_cvt_pk_bf16_f32 v73, v14, v15
	v_cvt_pk_bf16_f32 v74, v16, v17
	v_cvt_pk_bf16_f32 v75, v18, v19
	v_cvt_pk_bf16_f32 v76, v20, v21
	v_cvt_pk_bf16_f32 v77, v22, v23
	v_cvt_pk_bf16_f32 v78, v24, v25
	v_cvt_pk_bf16_f32 v79, v26, v27
	v_cvt_pk_bf16_f32 v80, v28, v29
	v_cvt_pk_bf16_f32 v81, v30, v31
	v_cvt_pk_bf16_f32 v82, v32, v33
	v_cvt_pk_bf16_f32 v83, v34, v35
	s_waitcnt lgkmcnt(6)
	v_pk_mul_f32 v[4:5], v[4:5], v[164:165]
	v_pk_mul_f32 v[6:7], v[6:7], v[166:167]
	v_pk_mul_f32 v[8:9], v[8:9], v[168:169]
	v_pk_mul_f32 v[10:11], v[10:11], v[170:171]
	v_pk_mul_f32 v[12:13], v[12:13], v[172:173]
	v_pk_mul_f32 v[14:15], v[14:15], v[174:175]
	v_pk_mul_f32 v[16:17], v[16:17], v[176:177]
	v_pk_mul_f32 v[18:19], v[18:19], v[178:179]
	v_pk_mul_f32 v[20:21], v[20:21], v[180:181]
	v_pk_mul_f32 v[22:23], v[22:23], v[182:183]
	v_pk_mul_f32 v[24:25], v[24:25], v[184:185]
	v_pk_mul_f32 v[26:27], v[26:27], v[186:187]
	v_pk_mul_f32 v[28:29], v[28:29], v[148:149]
	v_pk_mul_f32 v[30:31], v[30:31], v[150:151]
	v_pk_mul_f32 v[32:33], v[32:33], v[152:153]
	v_pk_mul_f32 v[34:35], v[34:35], v[154:155]
	ds_read_b128 v[108:111], v1 offset:8192
	ds_read_b128 v[112:115], v1 offset:9216
	ds_read_b128 v[116:119], v1 offset:10240
	ds_read_b128 v[120:123], v1 offset:11264
	ds_read_b128 v[124:127], v1 offset:12288
	ds_read_b128 v[128:131], v1 offset:13312
	ds_read_b128 v[132:135], v1 offset:14336
	ds_read_b128 v[136:139], v1 offset:15360
	s_waitcnt lgkmcnt(12)
	v_mfma_f32_16x16x32_bf16 v[196:199], v[88:91], v[84:87], 0
	s_waitcnt lgkmcnt(11)
	v_mfma_f32_16x16x32_bf16 v[196:199], v[92:95], v[68:71], v[196:199]
	s_waitcnt lgkmcnt(10)
	v_mfma_f32_16x16x32_bf16 v[196:199], v[96:99], v[72:75], v[196:199]
	s_waitcnt lgkmcnt(9)
	v_mfma_f32_16x16x32_bf16 v[196:199], v[100:103], v[76:79], v[196:199]
	s_waitcnt lgkmcnt(8)
	v_mfma_f32_16x16x32_bf16 v[196:199], v[104:107], v[80:83], v[196:199]
	s_waitcnt lgkmcnt(7)
	v_mfma_f32_16x16x32_bf16 v[4:7], v[108:111], v[84:87], v[4:7]
	s_waitcnt lgkmcnt(6)
	v_mfma_f32_16x16x32_bf16 v[8:11], v[112:115], v[84:87], v[8:11]
	s_waitcnt lgkmcnt(5)
	v_mfma_f32_16x16x32_bf16 v[12:15], v[116:119], v[84:87], v[12:15]
	s_waitcnt lgkmcnt(4)
	v_mfma_f32_16x16x32_bf16 v[16:19], v[120:123], v[84:87], v[16:19]
	s_waitcnt lgkmcnt(3)
	v_mfma_f32_16x16x32_bf16 v[20:23], v[124:127], v[84:87], v[20:23]
	s_waitcnt lgkmcnt(2)
	v_mfma_f32_16x16x32_bf16 v[24:27], v[128:131], v[84:87], v[24:27]
	s_waitcnt lgkmcnt(1)
	v_mfma_f32_16x16x32_bf16 v[28:31], v[132:135], v[84:87], v[28:31]
	s_waitcnt lgkmcnt(0)
; __device__ __forceinline__ void hg_chunk(const LAS unsigned char* sl, f32x4 (&S)[8], float* Orow, int nvalid, int vs, int lane) {
;     ...
; #pragma unroll
;     for (int i = 0; i < 4; ++i) { const int c0 = 4 * q + i;
;         if (c0 < nvalid) Orow[(size_t)c0 * DA + 16 * vs + r] = o0[i];
;         if (c0 + 16 < nvalid) Orow[(size_t)(c0 + 16) * DA + 16 * vs + r] = o1[i]; }
; __device__ __forceinline__ void hg_seq(const Frame& F, unsigned char* ws, const float* s0, float* sout, float* Og, int seq, bool sample, int vs_base, int nvs) {
;     ...
;     if (active) {
; #pragma unroll
;     for (int kb = 0; kb < 8; ++kb)
; #pragma unroll
;         for (int i = 0; i < 4; ++i) sout[((size_t)seq * 128 + 16 * kb + 4 * q + i) * 128 + 16 * vs + r] = S[kb][i];
	v_mfma_f32_16x16x32_bf16 v[32:35], v[136:139], v[84:87], v[32:35]
	s_mov_b32 exec_hi, 0
	global_store_dword v208, v196, s[12:13]
	global_store_dword v208, v197, s[12:13] offset:2048
	global_store_dword v209, v198, s[12:13]
	global_store_dword v209, v199, s[12:13] offset:2048
	s_mov_b64 exec, -1
	s_add_u32 s12, s12, 0x80000
	s_addc_u32 s13, s13, 0
	s_nop 7
	v_cndmask_b32_e64 v145, v4, v5, s[42:43]
	v_cndmask_b32_e64 v147, v6, v7, s[42:43]
	s_nop 1
	v_mov_b32_dpp v146, v145 quad_perm:[1,0,3,2] row_mask:0xf bank_mask:0xf
	v_mov_b32_dpp v156, v147 quad_perm:[1,0,3,2] row_mask:0xf bank_mask:0xf
	v_cndmask_b32_e64 v5, v5, v146, s[42:43]
	v_cndmask_b32_e64 v4, v146, v4, s[42:43]
	v_cndmask_b32_e64 v7, v7, v156, s[42:43]
	v_cndmask_b32_e64 v6, v156, v6, s[42:43]
	v_cndmask_b32_e64 v145, v4, v6, s[44:45]
	v_cndmask_b32_e64 v147, v5, v7, s[44:45]
	s_nop 1
	v_mov_b32_dpp v146, v145 quad_perm:[2,3,0,1] row_mask:0xf bank_mask:0xf
	v_mov_b32_dpp v156, v147 quad_perm:[2,3,0,1] row_mask:0xf bank_mask:0xf
	v_cndmask_b32_e64 v6, v6, v146, s[44:45]
	v_cndmask_b32_e64 v4, v146, v4, s[44:45]
	v_cndmask_b32_e64 v7, v7, v156, s[44:45]
	v_cndmask_b32_e64 v5, v156, v5, s[44:45]
	v_cndmask_b32_e64 v145, v8, v9, s[42:43]
	v_cndmask_b32_e64 v147, v10, v11, s[42:43]
	s_nop 1
	v_mov_b32_dpp v146, v145 quad_perm:[1,0,3,2] row_mask:0xf bank_mask:0xf
	v_mov_b32_dpp v156, v147 quad_perm:[1,0,3,2] row_mask:0xf bank_mask:0xf
	v_cndmask_b32_e64 v9, v9, v146, s[42:43]
	v_cndmask_b32_e64 v8, v146, v8, s[42:43]
	v_cndmask_b32_e64 v11, v11, v156, s[42:43]
	v_cndmask_b32_e64 v10, v156, v10, s[42:43]
	v_cndmask_b32_e64 v145, v8, v10, s[44:45]
	v_cndmask_b32_e64 v147, v9, v11, s[44:45]
	s_nop 1
	v_mov_b32_dpp v146, v145 quad_perm:[2,3,0,1] row_mask:0xf bank_mask:0xf
	v_mov_b32_dpp v156, v147 quad_perm:[2,3,0,1] row_mask:0xf bank_mask:0xf
	v_cndmask_b32_e64 v10, v10, v146, s[44:45]
	v_cndmask_b32_e64 v8, v146, v8, s[44:45]
	v_cndmask_b32_e64 v11, v11, v156, s[44:45]
	v_cndmask_b32_e64 v9, v156, v9, s[44:45]
	v_cndmask_b32_e64 v145, v12, v13, s[42:43]
	v_cndmask_b32_e64 v147, v14, v15, s[42:43]
	s_nop 1
	v_mov_b32_dpp v146, v145 quad_perm:[1,0,3,2] row_mask:0xf bank_mask:0xf
	v_mov_b32_dpp v156, v147 quad_perm:[1,0,3,2] row_mask:0xf bank_mask:0xf
	v_cndmask_b32_e64 v13, v13, v146, s[42:43]
	v_cndmask_b32_e64 v12, v146, v12, s[42:43]
	v_cndmask_b32_e64 v15, v15, v156, s[42:43]
	v_cndmask_b32_e64 v14, v156, v14, s[42:43]
	v_cndmask_b32_e64 v145, v12, v14, s[44:45]
	v_cndmask_b32_e64 v147, v13, v15, s[44:45]
	s_nop 1
	v_mov_b32_dpp v146, v145 quad_perm:[2,3,0,1] row_mask:0xf bank_mask:0xf
	v_mov_b32_dpp v156, v147 quad_perm:[2,3,0,1] row_mask:0xf bank_mask:0xf
	v_cndmask_b32_e64 v14, v14, v146, s[44:45]
	v_cndmask_b32_e64 v12, v146, v12, s[44:45]
	v_cndmask_b32_e64 v15, v15, v156, s[44:45]
	v_cndmask_b32_e64 v13, v156, v13, s[44:45]
	v_cndmask_b32_e64 v145, v16, v17, s[42:43]
	v_cndmask_b32_e64 v147, v18, v19, s[42:43]
	s_nop 1
	v_mov_b32_dpp v146, v145 quad_perm:[1,0,3,2] row_mask:0xf bank_mask:0xf
	v_mov_b32_dpp v156, v147 quad_perm:[1,0,3,2] row_mask:0xf bank_mask:0xf
	v_cndmask_b32_e64 v17, v17, v146, s[42:43]
	v_cndmask_b32_e64 v16, v146, v16, s[42:43]
	v_cndmask_b32_e64 v19, v19, v156, s[42:43]
	v_cndmask_b32_e64 v18, v156, v18, s[42:43]
	v_cndmask_b32_e64 v145, v16, v18, s[44:45]
	v_cndmask_b32_e64 v147, v17, v19, s[44:45]
	s_nop 1
	v_mov_b32_dpp v146, v145 quad_perm:[2,3,0,1] row_mask:0xf bank_mask:0xf
	v_mov_b32_dpp v156, v147 quad_perm:[2,3,0,1] row_mask:0xf bank_mask:0xf
	v_cndmask_b32_e64 v18, v18, v146, s[44:45]
	v_cndmask_b32_e64 v16, v146, v16, s[44:45]
	v_cndmask_b32_e64 v19, v19, v156, s[44:45]
	v_cndmask_b32_e64 v17, v156, v17, s[44:45]
	v_cndmask_b32_e64 v145, v20, v21, s[42:43]
	v_cndmask_b32_e64 v147, v22, v23, s[42:43]
	s_nop 1
	v_mov_b32_dpp v146, v145 quad_perm:[1,0,3,2] row_mask:0xf bank_mask:0xf
	v_mov_b32_dpp v156, v147 quad_perm:[1,0,3,2] row_mask:0xf bank_mask:0xf
	v_cndmask_b32_e64 v21, v21, v146, s[42:43]
	v_cndmask_b32_e64 v20, v146, v20, s[42:43]
	v_cndmask_b32_e64 v23, v23, v156, s[42:43]
	v_cndmask_b32_e64 v22, v156, v22, s[42:43]
	v_cndmask_b32_e64 v145, v20, v22, s[44:45]
	v_cndmask_b32_e64 v147, v21, v23, s[44:45]
	s_nop 1
	v_mov_b32_dpp v146, v145 quad_perm:[2,3,0,1] row_mask:0xf bank_mask:0xf
	v_mov_b32_dpp v156, v147 quad_perm:[2,3,0,1] row_mask:0xf bank_mask:0xf
	v_cndmask_b32_e64 v22, v22, v146, s[44:45]
	v_cndmask_b32_e64 v20, v146, v20, s[44:45]
	v_cndmask_b32_e64 v23, v23, v156, s[44:45]
	v_cndmask_b32_e64 v21, v156, v21, s[44:45]
	v_cndmask_b32_e64 v145, v24, v25, s[42:43]
	v_cndmask_b32_e64 v147, v26, v27, s[42:43]
	s_nop 1
	v_mov_b32_dpp v146, v145 quad_perm:[1,0,3,2] row_mask:0xf bank_mask:0xf
	v_mov_b32_dpp v156, v147 quad_perm:[1,0,3,2] row_mask:0xf bank_mask:0xf
	v_cndmask_b32_e64 v25, v25, v146, s[42:43]
	v_cndmask_b32_e64 v24, v146, v24, s[42:43]
	v_cndmask_b32_e64 v27, v27, v156, s[42:43]
	v_cndmask_b32_e64 v26, v156, v26, s[42:43]
	v_cndmask_b32_e64 v145, v24, v26, s[44:45]
	v_cndmask_b32_e64 v147, v25, v27, s[44:45]
	s_nop 1
	v_mov_b32_dpp v146, v145 quad_perm:[2,3,0,1] row_mask:0xf bank_mask:0xf
	v_mov_b32_dpp v156, v147 quad_perm:[2,3,0,1] row_mask:0xf bank_mask:0xf
	v_cndmask_b32_e64 v26, v26, v146, s[44:45]
	v_cndmask_b32_e64 v24, v146, v24, s[44:45]
	v_cndmask_b32_e64 v27, v27, v156, s[44:45]
	v_cndmask_b32_e64 v25, v156, v25, s[44:45]
	v_cndmask_b32_e64 v145, v28, v29, s[42:43]
	v_cndmask_b32_e64 v147, v30, v31, s[42:43]
	s_nop 1
	v_mov_b32_dpp v146, v145 quad_perm:[1,0,3,2] row_mask:0xf bank_mask:0xf
	v_mov_b32_dpp v156, v147 quad_perm:[1,0,3,2] row_mask:0xf bank_mask:0xf
	v_cndmask_b32_e64 v29, v29, v146, s[42:43]
; __device__ __forceinline__ void hg_seq(const Frame& F, unsigned char* ws, const float* s0, float* sout, float* Og, int seq, bool sample, int vs_base, int nvs) {
;     ...
;     if (sample && active) {
; #pragma unroll
;         for (int kb = 0; kb < 8; ++kb)
; #pragma unroll
;             for (int i = 0; i < 4; ++i) S[kb][i] = s0[((size_t)seq * 128 + 16 * kb + 4 * q + i) * 128 + 16 * vs + r];
;     ...
;     if (active) {
; #pragma unroll
;     for (int kb = 0; kb < 8; ++kb)
; #pragma unroll
;         for (int i = 0; i < 4; ++i) sout[((size_t)seq * 128 + 16 * kb + 4 * q + i) * 128 + 16 * vs + r] = S[kb][i];
	v_cndmask_b32_e64 v28, v146, v28, s[42:43]
	v_cndmask_b32_e64 v31, v31, v156, s[42:43]
	v_cndmask_b32_e64 v30, v156, v30, s[42:43]
	v_cndmask_b32_e64 v145, v28, v30, s[44:45]
	v_cndmask_b32_e64 v147, v29, v31, s[44:45]
	s_nop 1
	v_mov_b32_dpp v146, v145 quad_perm:[2,3,0,1] row_mask:0xf bank_mask:0xf
	v_mov_b32_dpp v156, v147 quad_perm:[2,3,0,1] row_mask:0xf bank_mask:0xf
	v_cndmask_b32_e64 v30, v30, v146, s[44:45]
	v_cndmask_b32_e64 v28, v146, v28, s[44:45]
	v_cndmask_b32_e64 v31, v31, v156, s[44:45]
	v_cndmask_b32_e64 v29, v156, v29, s[44:45]
	v_cndmask_b32_e64 v145, v32, v33, s[42:43]
	v_cndmask_b32_e64 v147, v34, v35, s[42:43]
	s_nop 1
	v_mov_b32_dpp v146, v145 quad_perm:[1,0,3,2] row_mask:0xf bank_mask:0xf
	v_mov_b32_dpp v156, v147 quad_perm:[1,0,3,2] row_mask:0xf bank_mask:0xf
	v_cndmask_b32_e64 v33, v33, v146, s[42:43]
	v_cndmask_b32_e64 v32, v146, v32, s[42:43]
	v_cndmask_b32_e64 v35, v35, v156, s[42:43]
	v_cndmask_b32_e64 v34, v156, v34, s[42:43]
	v_cndmask_b32_e64 v145, v32, v34, s[44:45]
	v_cndmask_b32_e64 v147, v33, v35, s[44:45]
	s_nop 1
	v_mov_b32_dpp v146, v145 quad_perm:[2,3,0,1] row_mask:0xf bank_mask:0xf
	v_mov_b32_dpp v156, v147 quad_perm:[2,3,0,1] row_mask:0xf bank_mask:0xf
	v_cndmask_b32_e64 v34, v34, v146, s[44:45]
	v_cndmask_b32_e64 v32, v146, v32, s[44:45]
	v_cndmask_b32_e64 v35, v35, v156, s[44:45]
	v_cndmask_b32_e64 v33, v156, v33, s[44:45]
	global_store_dwordx4 v200, v[4:7], s[10:11]
	global_store_dwordx4 v201, v[8:11], s[10:11]
	global_store_dwordx4 v202, v[12:15], s[10:11]
	global_store_dwordx4 v203, v[16:19], s[10:11]
	global_store_dwordx4 v204, v[20:23], s[10:11]
	global_store_dwordx4 v205, v[24:27], s[10:11]
	global_store_dwordx4 v206, v[28:31], s[10:11]
	global_store_dwordx4 v207, v[32:35], s[10:11]
	s_add_u32 s10, s10, s34
	s_addc_u32 s11, s11, 0
	s_waitcnt vmcnt(12)
	global_load_dwordx4 v[4:7], v200, s[8:9]
	global_load_dwordx4 v[8:11], v201, s[8:9]
	global_load_dwordx4 v[12:15], v202, s[8:9]
	global_load_dwordx4 v[16:19], v203, s[8:9]
	global_load_dwordx4 v[20:23], v204, s[8:9]
	global_load_dwordx4 v[24:27], v205, s[8:9]
	global_load_dwordx4 v[28:31], v206, s[8:9]
	global_load_dwordx4 v[32:35], v207, s[8:9]
	s_add_u32 s8, s8, s34
	s_addc_u32 s9, s9, 0
	v_cndmask_b32_e64 v145, v36, v37, s[42:43]
	v_cndmask_b32_e64 v147, v38, v39, s[42:43]
	s_nop 1
	v_mov_b32_dpp v146, v145 quad_perm:[1,0,3,2] row_mask:0xf bank_mask:0xf
	v_mov_b32_dpp v156, v147 quad_perm:[1,0,3,2] row_mask:0xf bank_mask:0xf
	v_cndmask_b32_e64 v37, v37, v146, s[42:43]
	v_cndmask_b32_e64 v36, v146, v36, s[42:43]
	v_cndmask_b32_e64 v39, v39, v156, s[42:43]
	v_cndmask_b32_e64 v38, v156, v38, s[42:43]
	v_cndmask_b32_e64 v145, v36, v38, s[44:45]
	v_cndmask_b32_e64 v147, v37, v39, s[44:45]
	s_nop 1
	v_mov_b32_dpp v146, v145 quad_perm:[2,3,0,1] row_mask:0xf bank_mask:0xf
	v_mov_b32_dpp v156, v147 quad_perm:[2,3,0,1] row_mask:0xf bank_mask:0xf
	v_cndmask_b32_e64 v38, v38, v146, s[44:45]
	v_cndmask_b32_e64 v36, v146, v36, s[44:45]
	v_cndmask_b32_e64 v39, v39, v156, s[44:45]
	v_cndmask_b32_e64 v37, v156, v37, s[44:45]
	v_cndmask_b32_e64 v145, v40, v41, s[42:43]
	v_cndmask_b32_e64 v147, v42, v43, s[42:43]
	s_nop 1
	v_mov_b32_dpp v146, v145 quad_perm:[1,0,3,2] row_mask:0xf bank_mask:0xf
	v_mov_b32_dpp v156, v147 quad_perm:[1,0,3,2] row_mask:0xf bank_mask:0xf
	v_cndmask_b32_e64 v41, v41, v146, s[42:43]
	v_cndmask_b32_e64 v40, v146, v40, s[42:43]
	v_cndmask_b32_e64 v43, v43, v156, s[42:43]
	v_cndmask_b32_e64 v42, v156, v42, s[42:43]
	v_cndmask_b32_e64 v145, v40, v42, s[44:45]
	v_cndmask_b32_e64 v147, v41, v43, s[44:45]
	s_nop 1
	v_mov_b32_dpp v146, v145 quad_perm:[2,3,0,1] row_mask:0xf bank_mask:0xf
	v_mov_b32_dpp v156, v147 quad_perm:[2,3,0,1] row_mask:0xf bank_mask:0xf
	v_cndmask_b32_e64 v42, v42, v146, s[44:45]
	v_cndmask_b32_e64 v40, v146, v40, s[44:45]
	v_cndmask_b32_e64 v43, v43, v156, s[44:45]
	v_cndmask_b32_e64 v41, v156, v41, s[44:45]
	v_cndmask_b32_e64 v145, v44, v45, s[42:43]
	v_cndmask_b32_e64 v147, v46, v47, s[42:43]
	s_nop 1
	v_mov_b32_dpp v146, v145 quad_perm:[1,0,3,2] row_mask:0xf bank_mask:0xf
	v_mov_b32_dpp v156, v147 quad_perm:[1,0,3,2] row_mask:0xf bank_mask:0xf
	v_cndmask_b32_e64 v45, v45, v146, s[42:43]
	v_cndmask_b32_e64 v44, v146, v44, s[42:43]
	v_cndmask_b32_e64 v47, v47, v156, s[42:43]
	v_cndmask_b32_e64 v46, v156, v46, s[42:43]
	v_cndmask_b32_e64 v145, v44, v46, s[44:45]
	v_cndmask_b32_e64 v147, v45, v47, s[44:45]
	s_nop 1
	v_mov_b32_dpp v146, v145 quad_perm:[2,3,0,1] row_mask:0xf bank_mask:0xf
	v_mov_b32_dpp v156, v147 quad_perm:[2,3,0,1] row_mask:0xf bank_mask:0xf
	v_cndmask_b32_e64 v46, v46, v146, s[44:45]
	v_cndmask_b32_e64 v44, v146, v44, s[44:45]
	v_cndmask_b32_e64 v47, v47, v156, s[44:45]
	v_cndmask_b32_e64 v45, v156, v45, s[44:45]
	v_cndmask_b32_e64 v145, v48, v49, s[42:43]
	v_cndmask_b32_e64 v147, v50, v51, s[42:43]
	s_nop 1
	v_mov_b32_dpp v146, v145 quad_perm:[1,0,3,2] row_mask:0xf bank_mask:0xf
	v_mov_b32_dpp v156, v147 quad_perm:[1,0,3,2] row_mask:0xf bank_mask:0xf
	v_cndmask_b32_e64 v49, v49, v146, s[42:43]
	v_cndmask_b32_e64 v48, v146, v48, s[42:43]
	v_cndmask_b32_e64 v51, v51, v156, s[42:43]
	v_cndmask_b32_e64 v50, v156, v50, s[42:43]
	v_cndmask_b32_e64 v145, v48, v50, s[44:45]
	v_cndmask_b32_e64 v147, v49, v51, s[44:45]
	s_nop 1
	v_mov_b32_dpp v146, v145 quad_perm:[2,3,0,1] row_mask:0xf bank_mask:0xf
	v_mov_b32_dpp v156, v147 quad_perm:[2,3,0,1] row_mask:0xf bank_mask:0xf
	v_cndmask_b32_e64 v50, v50, v146, s[44:45]
	v_cndmask_b32_e64 v48, v146, v48, s[44:45]
	v_cndmask_b32_e64 v51, v51, v156, s[44:45]
	v_cndmask_b32_e64 v49, v156, v49, s[44:45]
	v_cndmask_b32_e64 v145, v52, v53, s[42:43]
; #define LAS __attribute__((address_space(3)))
; __device__ __forceinline__ unsigned pk2(float lo, float hi) { const f32x2_t_ v = {lo, hi}; return __builtin_bit_cast(unsigned, __builtin_convertvector(v, bf16x2_t_)); }
; __device__ __forceinline__ void hg_chunk(const LAS unsigned char* sl, f32x4 (&S)[8], float* Orow, int nvalid, int vs, int lane) {
;     const int r = lane & 15, q = lane >> 4;
;     const bf16x8 vfr = *(const LAS bf16x8*)(sl + 16384 + ((vs * 64 + lane) << 4));
;     f32x4 o0 = {0.f, 0.f, 0.f, 0.f}, o1 = {0.f, 0.f, 0.f, 0.f};
;     { const bf16x8 s0 = *(const LAS bf16x8*)(sl + 24576 + (lane << 4)), s1 = *(const LAS bf16x8*)(sl + 24576 + ((64 + lane) << 4));
;       o0 = __builtin_amdgcn_mfma_f32_16x16x32_bf16(s0, vfr, o0, 0, 0, 0); o1 = __builtin_amdgcn_mfma_f32_16x16x32_bf16(s1, vfr, o1, 0, 0, 0); }
; #pragma unroll
;     for (int m = 0; m < 4; ++m) {
;         v4u sw; sw.x = pk2(S[2 * m][0], S[2 * m][1]); sw.y = pk2(S[2 * m][2], S[2 * m][3]); sw.z = pk2(S[2 * m + 1][0], S[2 * m + 1][1]); sw.w = pk2(S[2 * m + 1][2], S[2 * m + 1][3]);
;         const bf16x8 sb = __builtin_bit_cast(bf16x8, sw);
;         const bf16x8 a0 = *(const LAS bf16x8*)(sl + ((m * 64 + lane) << 4)), a1 = *(const LAS bf16x8*)(sl + (((4 + m) * 64 + lane) << 4));
;         o0 = __builtin_amdgcn_mfma_f32_16x16x32_bf16(a0, sb, o0, 0, 0, 0); o1 = __builtin_amdgcn_mfma_f32_16x16x32_bf16(a1, sb, o1, 0, 0, 0);
;     }
; #pragma unroll
;     for (int i = 0; i < 4; ++i) { const int c0 = 4 * q + i;
;         if (c0 < nvalid) Orow[(size_t)c0 * DA + 16 * vs + r] = o0[i];
;         if (c0 + 16 < nvalid) Orow[(size_t)(c0 + 16) * DA + 16 * vs + r] = o1[i]; }
; #pragma unroll
;     for (int kb = 0; kb < 8; ++kb) { const f32x4 d = *(const LAS f32x4*)(sl + 26624 + ((16 * kb + 4 * q) << 2));
;         const bf16x8 ke = *(const LAS bf16x8*)(sl + 8192 + ((kb * 64 + lane) << 4));
;         S[kb] = __builtin_amdgcn_mfma_f32_16x16x32_bf16(ke, vfr, S[kb] * d, 0, 0, 0); }
	v_cndmask_b32_e64 v147, v54, v55, s[42:43]
	s_nop 1
	v_mov_b32_dpp v146, v145 quad_perm:[1,0,3,2] row_mask:0xf bank_mask:0xf
	v_mov_b32_dpp v156, v147 quad_perm:[1,0,3,2] row_mask:0xf bank_mask:0xf
	v_cndmask_b32_e64 v53, v53, v146, s[42:43]
	v_cndmask_b32_e64 v52, v146, v52, s[42:43]
	v_cndmask_b32_e64 v55, v55, v156, s[42:43]
	v_cndmask_b32_e64 v54, v156, v54, s[42:43]
	v_cndmask_b32_e64 v145, v52, v54, s[44:45]
	v_cndmask_b32_e64 v147, v53, v55, s[44:45]
	s_nop 1
	v_mov_b32_dpp v146, v145 quad_perm:[2,3,0,1] row_mask:0xf bank_mask:0xf
	v_mov_b32_dpp v156, v147 quad_perm:[2,3,0,1] row_mask:0xf bank_mask:0xf
	v_cndmask_b32_e64 v54, v54, v146, s[44:45]
	v_cndmask_b32_e64 v52, v146, v52, s[44:45]
	v_cndmask_b32_e64 v55, v55, v156, s[44:45]
	v_cndmask_b32_e64 v53, v156, v53, s[44:45]
	v_cndmask_b32_e64 v145, v56, v57, s[42:43]
	v_cndmask_b32_e64 v147, v58, v59, s[42:43]
	s_nop 1
	v_mov_b32_dpp v146, v145 quad_perm:[1,0,3,2] row_mask:0xf bank_mask:0xf
	v_mov_b32_dpp v156, v147 quad_perm:[1,0,3,2] row_mask:0xf bank_mask:0xf
	v_cndmask_b32_e64 v57, v57, v146, s[42:43]
	v_cndmask_b32_e64 v56, v146, v56, s[42:43]
	v_cndmask_b32_e64 v59, v59, v156, s[42:43]
	v_cndmask_b32_e64 v58, v156, v58, s[42:43]
	v_cndmask_b32_e64 v145, v56, v58, s[44:45]
	v_cndmask_b32_e64 v147, v57, v59, s[44:45]
	s_nop 1
	v_mov_b32_dpp v146, v145 quad_perm:[2,3,0,1] row_mask:0xf bank_mask:0xf
	v_mov_b32_dpp v156, v147 quad_perm:[2,3,0,1] row_mask:0xf bank_mask:0xf
	v_cndmask_b32_e64 v58, v58, v146, s[44:45]
	v_cndmask_b32_e64 v56, v146, v56, s[44:45]
	v_cndmask_b32_e64 v59, v59, v156, s[44:45]
	v_cndmask_b32_e64 v57, v156, v57, s[44:45]
	v_cndmask_b32_e64 v145, v60, v61, s[42:43]
	v_cndmask_b32_e64 v147, v62, v63, s[42:43]
	s_nop 1
	v_mov_b32_dpp v146, v145 quad_perm:[1,0,3,2] row_mask:0xf bank_mask:0xf
	v_mov_b32_dpp v156, v147 quad_perm:[1,0,3,2] row_mask:0xf bank_mask:0xf
	v_cndmask_b32_e64 v61, v61, v146, s[42:43]
	v_cndmask_b32_e64 v60, v146, v60, s[42:43]
	v_cndmask_b32_e64 v63, v63, v156, s[42:43]
	v_cndmask_b32_e64 v62, v156, v62, s[42:43]
	v_cndmask_b32_e64 v145, v60, v62, s[44:45]
	v_cndmask_b32_e64 v147, v61, v63, s[44:45]
	s_nop 1
	v_mov_b32_dpp v146, v145 quad_perm:[2,3,0,1] row_mask:0xf bank_mask:0xf
	v_mov_b32_dpp v156, v147 quad_perm:[2,3,0,1] row_mask:0xf bank_mask:0xf
	v_cndmask_b32_e64 v62, v62, v146, s[44:45]
	v_cndmask_b32_e64 v60, v146, v60, s[44:45]
	v_cndmask_b32_e64 v63, v63, v156, s[44:45]
	v_cndmask_b32_e64 v61, v156, v61, s[44:45]
	v_cndmask_b32_e64 v145, v64, v65, s[42:43]
	v_cndmask_b32_e64 v147, v66, v67, s[42:43]
	s_nop 1
	v_mov_b32_dpp v146, v145 quad_perm:[1,0,3,2] row_mask:0xf bank_mask:0xf
	v_mov_b32_dpp v156, v147 quad_perm:[1,0,3,2] row_mask:0xf bank_mask:0xf
	v_cndmask_b32_e64 v65, v65, v146, s[42:43]
	v_cndmask_b32_e64 v64, v146, v64, s[42:43]
	v_cndmask_b32_e64 v67, v67, v156, s[42:43]
	v_cndmask_b32_e64 v66, v156, v66, s[42:43]
	v_cndmask_b32_e64 v145, v64, v66, s[44:45]
	v_cndmask_b32_e64 v147, v65, v67, s[44:45]
	s_nop 1
	v_mov_b32_dpp v146, v145 quad_perm:[2,3,0,1] row_mask:0xf bank_mask:0xf
	v_mov_b32_dpp v156, v147 quad_perm:[2,3,0,1] row_mask:0xf bank_mask:0xf
	v_cndmask_b32_e64 v66, v66, v146, s[44:45]
	v_cndmask_b32_e64 v64, v146, v64, s[44:45]
	v_cndmask_b32_e64 v67, v67, v156, s[44:45]
	v_cndmask_b32_e64 v65, v156, v65, s[44:45]
	v_add_u32_e32 v1, 0x6c00, v142
	v_add_u32_e32 v2, 0x6c00, v143
	v_add_u32_e32 v3, 0x6c00, v144
	ds_read_b128 v[164:167], v3 offset:26624
	ds_read_b128 v[168:171], v3 offset:26688
	ds_read_b128 v[172:175], v3 offset:26752
	ds_read_b128 v[176:179], v3 offset:26816
	ds_read_b128 v[180:183], v3 offset:26880
	ds_read_b128 v[184:187], v3 offset:26944
	ds_read_b128 v[148:151], v3 offset:27008
	ds_read_b128 v[152:155], v3 offset:27072
	ds_read_b128 v[84:87], v2 offset:16384
	ds_read_b128 v[88:91], v1 offset:24576
	ds_read_b128 v[92:95], v1 offset:0
	ds_read_b128 v[96:99], v1 offset:1024
	ds_read_b128 v[100:103], v1 offset:2048
	ds_read_b128 v[104:107], v1 offset:3072
	v_cvt_pk_bf16_f32 v68, v36, v37
	v_cvt_pk_bf16_f32 v69, v38, v39
	v_cvt_pk_bf16_f32 v70, v40, v41
	v_cvt_pk_bf16_f32 v71, v42, v43
	v_cvt_pk_bf16_f32 v72, v44, v45
	v_cvt_pk_bf16_f32 v73, v46, v47
	v_cvt_pk_bf16_f32 v74, v48, v49
	v_cvt_pk_bf16_f32 v75, v50, v51
	v_cvt_pk_bf16_f32 v76, v52, v53
	v_cvt_pk_bf16_f32 v77, v54, v55
	v_cvt_pk_bf16_f32 v78, v56, v57
	v_cvt_pk_bf16_f32 v79, v58, v59
	v_cvt_pk_bf16_f32 v80, v60, v61
	v_cvt_pk_bf16_f32 v81, v62, v63
	v_cvt_pk_bf16_f32 v82, v64, v65
	v_cvt_pk_bf16_f32 v83, v66, v67
	s_waitcnt lgkmcnt(6)
	v_pk_mul_f32 v[36:37], v[36:37], v[164:165]
	v_pk_mul_f32 v[38:39], v[38:39], v[166:167]
	v_pk_mul_f32 v[40:41], v[40:41], v[168:169]
	v_pk_mul_f32 v[42:43], v[42:43], v[170:171]
	v_pk_mul_f32 v[44:45], v[44:45], v[172:173]
	v_pk_mul_f32 v[46:47], v[46:47], v[174:175]
	v_pk_mul_f32 v[48:49], v[48:49], v[176:177]
	v_pk_mul_f32 v[50:51], v[50:51], v[178:179]
	v_pk_mul_f32 v[52:53], v[52:53], v[180:181]
	v_pk_mul_f32 v[54:55], v[54:55], v[182:183]
	v_pk_mul_f32 v[56:57], v[56:57], v[184:185]
	v_pk_mul_f32 v[58:59], v[58:59], v[186:187]
	v_pk_mul_f32 v[60:61], v[60:61], v[148:149]
	v_pk_mul_f32 v[62:63], v[62:63], v[150:151]
	v_pk_mul_f32 v[64:65], v[64:65], v[152:153]
	v_pk_mul_f32 v[66:67], v[66:67], v[154:155]
	ds_read_b128 v[108:111], v1 offset:8192
	ds_read_b128 v[112:115], v1 offset:9216
	ds_read_b128 v[116:119], v1 offset:10240
	ds_read_b128 v[120:123], v1 offset:11264
	ds_read_b128 v[124:127], v1 offset:12288
	ds_read_b128 v[128:131], v1 offset:13312
	ds_read_b128 v[132:135], v1 offset:14336
	ds_read_b128 v[136:139], v1 offset:15360
	s_waitcnt lgkmcnt(12)
; #define LAS __attribute__((address_space(3)))
; __device__ __forceinline__ unsigned pk2(float lo, float hi) { const f32x2_t_ v = {lo, hi}; return __builtin_bit_cast(unsigned, __builtin_convertvector(v, bf16x2_t_)); }
; __device__ __forceinline__ void hg_chunk(const LAS unsigned char* sl, f32x4 (&S)[8], float* Orow, int nvalid, int vs, int lane) {
;     ...
;       o0 = __builtin_amdgcn_mfma_f32_16x16x32_bf16(s0, vfr, o0, 0, 0, 0); o1 = __builtin_amdgcn_mfma_f32_16x16x32_bf16(s1, vfr, o1, 0, 0, 0); }
; #pragma unroll
;     for (int m = 0; m < 4; ++m) {
;         v4u sw; sw.x = pk2(S[2 * m][0], S[2 * m][1]); sw.y = pk2(S[2 * m][2], S[2 * m][3]); sw.z = pk2(S[2 * m + 1][0], S[2 * m + 1][1]); sw.w = pk2(S[2 * m + 1][2], S[2 * m + 1][3]);
;         const bf16x8 sb = __builtin_bit_cast(bf16x8, sw);
;         const bf16x8 a0 = *(const LAS bf16x8*)(sl + ((m * 64 + lane) << 4)), a1 = *(const LAS bf16x8*)(sl + (((4 + m) * 64 + lane) << 4));
;         o0 = __builtin_amdgcn_mfma_f32_16x16x32_bf16(a0, sb, o0, 0, 0, 0); o1 = __builtin_amdgcn_mfma_f32_16x16x32_bf16(a1, sb, o1, 0, 0, 0);
;     }
; #pragma unroll
;     for (int i = 0; i < 4; ++i) { const int c0 = 4 * q + i;
;         if (c0 < nvalid) Orow[(size_t)c0 * DA + 16 * vs + r] = o0[i];
;         if (c0 + 16 < nvalid) Orow[(size_t)(c0 + 16) * DA + 16 * vs + r] = o1[i]; }
; #pragma unroll
;     for (int kb = 0; kb < 8; ++kb) { const f32x4 d = *(const LAS f32x4*)(sl + 26624 + ((16 * kb + 4 * q) << 2));
;         const bf16x8 ke = *(const LAS bf16x8*)(sl + 8192 + ((kb * 64 + lane) << 4));
;         S[kb] = __builtin_amdgcn_mfma_f32_16x16x32_bf16(ke, vfr, S[kb] * d, 0, 0, 0); }
; __device__ __forceinline__ void hg_seq(const Frame& F, unsigned char* ws, const float* s0, float* sout, float* Og, int seq, bool sample, int vs_base, int nvs) {
;     ...
;     if (active) {
; #pragma unroll
;     for (int kb = 0; kb < 8; ++kb)
; #pragma unroll
;         for (int i = 0; i < 4; ++i) sout[((size_t)seq * 128 + 16 * kb + 4 * q + i) * 128 + 16 * vs + r] = S[kb][i];
	v_mfma_f32_16x16x32_bf16 v[196:199], v[88:91], v[84:87], 0
	s_waitcnt lgkmcnt(11)
	v_mfma_f32_16x16x32_bf16 v[196:199], v[92:95], v[68:71], v[196:199]
	s_waitcnt lgkmcnt(10)
	v_mfma_f32_16x16x32_bf16 v[196:199], v[96:99], v[72:75], v[196:199]
	s_waitcnt lgkmcnt(9)
	v_mfma_f32_16x16x32_bf16 v[196:199], v[100:103], v[76:79], v[196:199]
	s_waitcnt lgkmcnt(8)
	v_mfma_f32_16x16x32_bf16 v[196:199], v[104:107], v[80:83], v[196:199]
	s_waitcnt lgkmcnt(7)
	v_mfma_f32_16x16x32_bf16 v[36:39], v[108:111], v[84:87], v[36:39]
	s_waitcnt lgkmcnt(6)
	v_mfma_f32_16x16x32_bf16 v[40:43], v[112:115], v[84:87], v[40:43]
	s_waitcnt lgkmcnt(5)
	v_mfma_f32_16x16x32_bf16 v[44:47], v[116:119], v[84:87], v[44:47]
	s_waitcnt lgkmcnt(4)
	v_mfma_f32_16x16x32_bf16 v[48:51], v[120:123], v[84:87], v[48:51]
	s_waitcnt lgkmcnt(3)
	v_mfma_f32_16x16x32_bf16 v[52:55], v[124:127], v[84:87], v[52:55]
	s_waitcnt lgkmcnt(2)
	v_mfma_f32_16x16x32_bf16 v[56:59], v[128:131], v[84:87], v[56:59]
	s_waitcnt lgkmcnt(1)
	v_mfma_f32_16x16x32_bf16 v[60:63], v[132:135], v[84:87], v[60:63]
	s_waitcnt lgkmcnt(0)
	v_mfma_f32_16x16x32_bf16 v[64:67], v[136:139], v[84:87], v[64:67]
	s_mov_b32 exec_hi, 0
	global_store_dword v208, v196, s[12:13]
	global_store_dword v208, v197, s[12:13] offset:2048
	global_store_dword v209, v198, s[12:13]
	global_store_dword v209, v199, s[12:13] offset:2048
	s_mov_b64 exec, -1
	s_add_u32 s12, s12, 0x80000
	s_addc_u32 s13, s13, 0
	s_nop 7
	v_cndmask_b32_e64 v145, v36, v37, s[42:43]
	v_cndmask_b32_e64 v147, v38, v39, s[42:43]
	s_nop 1
	v_mov_b32_dpp v146, v145 quad_perm:[1,0,3,2] row_mask:0xf bank_mask:0xf
	v_mov_b32_dpp v156, v147 quad_perm:[1,0,3,2] row_mask:0xf bank_mask:0xf
	v_cndmask_b32_e64 v37, v37, v146, s[42:43]
	v_cndmask_b32_e64 v36, v146, v36, s[42:43]
	v_cndmask_b32_e64 v39, v39, v156, s[42:43]
	v_cndmask_b32_e64 v38, v156, v38, s[42:43]
	v_cndmask_b32_e64 v145, v36, v38, s[44:45]
	v_cndmask_b32_e64 v147, v37, v39, s[44:45]
	s_nop 1
	v_mov_b32_dpp v146, v145 quad_perm:[2,3,0,1] row_mask:0xf bank_mask:0xf
	v_mov_b32_dpp v156, v147 quad_perm:[2,3,0,1] row_mask:0xf bank_mask:0xf
	v_cndmask_b32_e64 v38, v38, v146, s[44:45]
	v_cndmask_b32_e64 v36, v146, v36, s[44:45]
	v_cndmask_b32_e64 v39, v39, v156, s[44:45]
	v_cndmask_b32_e64 v37, v156, v37, s[44:45]
	v_cndmask_b32_e64 v145, v40, v41, s[42:43]
	v_cndmask_b32_e64 v147, v42, v43, s[42:43]
	s_nop 1
	v_mov_b32_dpp v146, v145 quad_perm:[1,0,3,2] row_mask:0xf bank_mask:0xf
	v_mov_b32_dpp v156, v147 quad_perm:[1,0,3,2] row_mask:0xf bank_mask:0xf
	v_cndmask_b32_e64 v41, v41, v146, s[42:43]
	v_cndmask_b32_e64 v40, v146, v40, s[42:43]
	v_cndmask_b32_e64 v43, v43, v156, s[42:43]
	v_cndmask_b32_e64 v42, v156, v42, s[42:43]
	v_cndmask_b32_e64 v145, v40, v42, s[44:45]
	v_cndmask_b32_e64 v147, v41, v43, s[44:45]
	s_nop 1
	v_mov_b32_dpp v146, v145 quad_perm:[2,3,0,1] row_mask:0xf bank_mask:0xf
	v_mov_b32_dpp v156, v147 quad_perm:[2,3,0,1] row_mask:0xf bank_mask:0xf
	v_cndmask_b32_e64 v42, v42, v146, s[44:45]
	v_cndmask_b32_e64 v40, v146, v40, s[44:45]
	v_cndmask_b32_e64 v43, v43, v156, s[44:45]
	v_cndmask_b32_e64 v41, v156, v41, s[44:45]
	v_cndmask_b32_e64 v145, v44, v45, s[42:43]
	v_cndmask_b32_e64 v147, v46, v47, s[42:43]
	s_nop 1
	v_mov_b32_dpp v146, v145 quad_perm:[1,0,3,2] row_mask:0xf bank_mask:0xf
	v_mov_b32_dpp v156, v147 quad_perm:[1,0,3,2] row_mask:0xf bank_mask:0xf
	v_cndmask_b32_e64 v45, v45, v146, s[42:43]
	v_cndmask_b32_e64 v44, v146, v44, s[42:43]
	v_cndmask_b32_e64 v47, v47, v156, s[42:43]
	v_cndmask_b32_e64 v46, v156, v46, s[42:43]
	v_cndmask_b32_e64 v145, v44, v46, s[44:45]
	v_cndmask_b32_e64 v147, v45, v47, s[44:45]
	s_nop 1
	v_mov_b32_dpp v146, v145 quad_perm:[2,3,0,1] row_mask:0xf bank_mask:0xf
	v_mov_b32_dpp v156, v147 quad_perm:[2,3,0,1] row_mask:0xf bank_mask:0xf
	v_cndmask_b32_e64 v46, v46, v146, s[44:45]
	v_cndmask_b32_e64 v44, v146, v44, s[44:45]
	v_cndmask_b32_e64 v47, v47, v156, s[44:45]
	v_cndmask_b32_e64 v45, v156, v45, s[44:45]
	v_cndmask_b32_e64 v145, v48, v49, s[42:43]
	v_cndmask_b32_e64 v147, v50, v51, s[42:43]
	s_nop 1
	v_mov_b32_dpp v146, v145 quad_perm:[1,0,3,2] row_mask:0xf bank_mask:0xf
	v_mov_b32_dpp v156, v147 quad_perm:[1,0,3,2] row_mask:0xf bank_mask:0xf
	v_cndmask_b32_e64 v49, v49, v146, s[42:43]
	v_cndmask_b32_e64 v48, v146, v48, s[42:43]
	v_cndmask_b32_e64 v51, v51, v156, s[42:43]
	v_cndmask_b32_e64 v50, v156, v50, s[42:43]
	v_cndmask_b32_e64 v145, v48, v50, s[44:45]
	v_cndmask_b32_e64 v147, v49, v51, s[44:45]
	s_nop 1
	v_mov_b32_dpp v146, v145 quad_perm:[2,3,0,1] row_mask:0xf bank_mask:0xf
	v_mov_b32_dpp v156, v147 quad_perm:[2,3,0,1] row_mask:0xf bank_mask:0xf
	v_cndmask_b32_e64 v50, v50, v146, s[44:45]
	v_cndmask_b32_e64 v48, v146, v48, s[44:45]
	v_cndmask_b32_e64 v51, v51, v156, s[44:45]
	v_cndmask_b32_e64 v49, v156, v49, s[44:45]
	v_cndmask_b32_e64 v145, v52, v53, s[42:43]
	v_cndmask_b32_e64 v147, v54, v55, s[42:43]
	s_nop 1
	v_mov_b32_dpp v146, v145 quad_perm:[1,0,3,2] row_mask:0xf bank_mask:0xf
	v_mov_b32_dpp v156, v147 quad_perm:[1,0,3,2] row_mask:0xf bank_mask:0xf
	v_cndmask_b32_e64 v53, v53, v146, s[42:43]
	v_cndmask_b32_e64 v52, v146, v52, s[42:43]
	v_cndmask_b32_e64 v55, v55, v156, s[42:43]
	v_cndmask_b32_e64 v54, v156, v54, s[42:43]
	v_cndmask_b32_e64 v145, v52, v54, s[44:45]
	v_cndmask_b32_e64 v147, v53, v55, s[44:45]
	s_nop 1
	v_mov_b32_dpp v146, v145 quad_perm:[2,3,0,1] row_mask:0xf bank_mask:0xf
	v_mov_b32_dpp v156, v147 quad_perm:[2,3,0,1] row_mask:0xf bank_mask:0xf
	v_cndmask_b32_e64 v54, v54, v146, s[44:45]
	v_cndmask_b32_e64 v52, v146, v52, s[44:45]
	v_cndmask_b32_e64 v55, v55, v156, s[44:45]
	v_cndmask_b32_e64 v53, v156, v53, s[44:45]
; __device__ __forceinline__ void hg_seq(const Frame& F, unsigned char* ws, const float* s0, float* sout, float* Og, int seq, bool sample, int vs_base, int nvs) {
;     ...
;     if (sample && active) {
; #pragma unroll
;         for (int kb = 0; kb < 8; ++kb)
; #pragma unroll
;             for (int i = 0; i < 4; ++i) S[kb][i] = s0[((size_t)seq * 128 + 16 * kb + 4 * q + i) * 128 + 16 * vs + r];
;     ...
;     if (active) {
; #pragma unroll
;     for (int kb = 0; kb < 8; ++kb)
; #pragma unroll
;         for (int i = 0; i < 4; ++i) sout[((size_t)seq * 128 + 16 * kb + 4 * q + i) * 128 + 16 * vs + r] = S[kb][i];
	v_cndmask_b32_e64 v145, v56, v57, s[42:43]
	v_cndmask_b32_e64 v147, v58, v59, s[42:43]
	s_nop 1
	v_mov_b32_dpp v146, v145 quad_perm:[1,0,3,2] row_mask:0xf bank_mask:0xf
	v_mov_b32_dpp v156, v147 quad_perm:[1,0,3,2] row_mask:0xf bank_mask:0xf
	v_cndmask_b32_e64 v57, v57, v146, s[42:43]
	v_cndmask_b32_e64 v56, v146, v56, s[42:43]
	v_cndmask_b32_e64 v59, v59, v156, s[42:43]
	v_cndmask_b32_e64 v58, v156, v58, s[42:43]
	v_cndmask_b32_e64 v145, v56, v58, s[44:45]
	v_cndmask_b32_e64 v147, v57, v59, s[44:45]
	s_nop 1
	v_mov_b32_dpp v146, v145 quad_perm:[2,3,0,1] row_mask:0xf bank_mask:0xf
	v_mov_b32_dpp v156, v147 quad_perm:[2,3,0,1] row_mask:0xf bank_mask:0xf
	v_cndmask_b32_e64 v58, v58, v146, s[44:45]
	v_cndmask_b32_e64 v56, v146, v56, s[44:45]
	v_cndmask_b32_e64 v59, v59, v156, s[44:45]
	v_cndmask_b32_e64 v57, v156, v57, s[44:45]
	v_cndmask_b32_e64 v145, v60, v61, s[42:43]
	v_cndmask_b32_e64 v147, v62, v63, s[42:43]
	s_nop 1
	v_mov_b32_dpp v146, v145 quad_perm:[1,0,3,2] row_mask:0xf bank_mask:0xf
	v_mov_b32_dpp v156, v147 quad_perm:[1,0,3,2] row_mask:0xf bank_mask:0xf
	v_cndmask_b32_e64 v61, v61, v146, s[42:43]
	v_cndmask_b32_e64 v60, v146, v60, s[42:43]
	v_cndmask_b32_e64 v63, v63, v156, s[42:43]
	v_cndmask_b32_e64 v62, v156, v62, s[42:43]
	v_cndmask_b32_e64 v145, v60, v62, s[44:45]
	v_cndmask_b32_e64 v147, v61, v63, s[44:45]
	s_nop 1
	v_mov_b32_dpp v146, v145 quad_perm:[2,3,0,1] row_mask:0xf bank_mask:0xf
	v_mov_b32_dpp v156, v147 quad_perm:[2,3,0,1] row_mask:0xf bank_mask:0xf
	v_cndmask_b32_e64 v62, v62, v146, s[44:45]
	v_cndmask_b32_e64 v60, v146, v60, s[44:45]
	v_cndmask_b32_e64 v63, v63, v156, s[44:45]
	v_cndmask_b32_e64 v61, v156, v61, s[44:45]
	v_cndmask_b32_e64 v145, v64, v65, s[42:43]
	v_cndmask_b32_e64 v147, v66, v67, s[42:43]
	s_nop 1
	v_mov_b32_dpp v146, v145 quad_perm:[1,0,3,2] row_mask:0xf bank_mask:0xf
	v_mov_b32_dpp v156, v147 quad_perm:[1,0,3,2] row_mask:0xf bank_mask:0xf
	v_cndmask_b32_e64 v65, v65, v146, s[42:43]
	v_cndmask_b32_e64 v64, v146, v64, s[42:43]
	v_cndmask_b32_e64 v67, v67, v156, s[42:43]
	v_cndmask_b32_e64 v66, v156, v66, s[42:43]
	v_cndmask_b32_e64 v145, v64, v66, s[44:45]
	v_cndmask_b32_e64 v147, v65, v67, s[44:45]
	s_nop 1
	v_mov_b32_dpp v146, v145 quad_perm:[2,3,0,1] row_mask:0xf bank_mask:0xf
	v_mov_b32_dpp v156, v147 quad_perm:[2,3,0,1] row_mask:0xf bank_mask:0xf
	v_cndmask_b32_e64 v66, v66, v146, s[44:45]
	v_cndmask_b32_e64 v64, v146, v64, s[44:45]
	v_cndmask_b32_e64 v67, v67, v156, s[44:45]
	v_cndmask_b32_e64 v65, v156, v65, s[44:45]
	global_store_dwordx4 v200, v[36:39], s[10:11]
	global_store_dwordx4 v201, v[40:43], s[10:11]
	global_store_dwordx4 v202, v[44:47], s[10:11]
	global_store_dwordx4 v203, v[48:51], s[10:11]
	global_store_dwordx4 v204, v[52:55], s[10:11]
	global_store_dwordx4 v205, v[56:59], s[10:11]
	global_store_dwordx4 v206, v[60:63], s[10:11]
	global_store_dwordx4 v207, v[64:67], s[10:11]
	s_add_u32 s10, s10, s34
	s_addc_u32 s11, s11, 0
	s_waitcnt vmcnt(12)
	v_cndmask_b32_e64 v145, v4, v5, s[42:43]
	v_cndmask_b32_e64 v147, v6, v7, s[42:43]
	s_nop 1
	v_mov_b32_dpp v146, v145 quad_perm:[1,0,3,2] row_mask:0xf bank_mask:0xf
	v_mov_b32_dpp v156, v147 quad_perm:[1,0,3,2] row_mask:0xf bank_mask:0xf
	v_cndmask_b32_e64 v5, v5, v146, s[42:43]
	v_cndmask_b32_e64 v4, v146, v4, s[42:43]
	v_cndmask_b32_e64 v7, v7, v156, s[42:43]
	v_cndmask_b32_e64 v6, v156, v6, s[42:43]
	v_cndmask_b32_e64 v145, v4, v6, s[44:45]
	v_cndmask_b32_e64 v147, v5, v7, s[44:45]
	s_nop 1
	v_mov_b32_dpp v146, v145 quad_perm:[2,3,0,1] row_mask:0xf bank_mask:0xf
	v_mov_b32_dpp v156, v147 quad_perm:[2,3,0,1] row_mask:0xf bank_mask:0xf
	v_cndmask_b32_e64 v6, v6, v146, s[44:45]
	v_cndmask_b32_e64 v4, v146, v4, s[44:45]
	v_cndmask_b32_e64 v7, v7, v156, s[44:45]
	v_cndmask_b32_e64 v5, v156, v5, s[44:45]
	v_cndmask_b32_e64 v145, v8, v9, s[42:43]
	v_cndmask_b32_e64 v147, v10, v11, s[42:43]
	s_nop 1
	v_mov_b32_dpp v146, v145 quad_perm:[1,0,3,2] row_mask:0xf bank_mask:0xf
	v_mov_b32_dpp v156, v147 quad_perm:[1,0,3,2] row_mask:0xf bank_mask:0xf
	v_cndmask_b32_e64 v9, v9, v146, s[42:43]
	v_cndmask_b32_e64 v8, v146, v8, s[42:43]
	v_cndmask_b32_e64 v11, v11, v156, s[42:43]
	v_cndmask_b32_e64 v10, v156, v10, s[42:43]
	v_cndmask_b32_e64 v145, v8, v10, s[44:45]
	v_cndmask_b32_e64 v147, v9, v11, s[44:45]
	s_nop 1
	v_mov_b32_dpp v146, v145 quad_perm:[2,3,0,1] row_mask:0xf bank_mask:0xf
	v_mov_b32_dpp v156, v147 quad_perm:[2,3,0,1] row_mask:0xf bank_mask:0xf
	v_cndmask_b32_e64 v10, v10, v146, s[44:45]
	v_cndmask_b32_e64 v8, v146, v8, s[44:45]
	v_cndmask_b32_e64 v11, v11, v156, s[44:45]
	v_cndmask_b32_e64 v9, v156, v9, s[44:45]
	v_cndmask_b32_e64 v145, v12, v13, s[42:43]
	v_cndmask_b32_e64 v147, v14, v15, s[42:43]
	s_nop 1
	v_mov_b32_dpp v146, v145 quad_perm:[1,0,3,2] row_mask:0xf bank_mask:0xf
	v_mov_b32_dpp v156, v147 quad_perm:[1,0,3,2] row_mask:0xf bank_mask:0xf
	v_cndmask_b32_e64 v13, v13, v146, s[42:43]
	v_cndmask_b32_e64 v12, v146, v12, s[42:43]
	v_cndmask_b32_e64 v15, v15, v156, s[42:43]
	v_cndmask_b32_e64 v14, v156, v14, s[42:43]
	v_cndmask_b32_e64 v145, v12, v14, s[44:45]
	v_cndmask_b32_e64 v147, v13, v15, s[44:45]
	s_nop 1
	v_mov_b32_dpp v146, v145 quad_perm:[2,3,0,1] row_mask:0xf bank_mask:0xf
	v_mov_b32_dpp v156, v147 quad_perm:[2,3,0,1] row_mask:0xf bank_mask:0xf
	v_cndmask_b32_e64 v14, v14, v146, s[44:45]
	v_cndmask_b32_e64 v12, v146, v12, s[44:45]
	v_cndmask_b32_e64 v15, v15, v156, s[44:45]
	v_cndmask_b32_e64 v13, v156, v13, s[44:45]
	v_cndmask_b32_e64 v145, v16, v17, s[42:43]
	v_cndmask_b32_e64 v147, v18, v19, s[42:43]
	s_nop 1
	v_mov_b32_dpp v146, v145 quad_perm:[1,0,3,2] row_mask:0xf bank_mask:0xf
; #define LAS __attribute__((address_space(3)))
; __device__ __forceinline__ unsigned pk2(float lo, float hi) { const f32x2_t_ v = {lo, hi}; return __builtin_bit_cast(unsigned, __builtin_convertvector(v, bf16x2_t_)); }
; __device__ __forceinline__ void hg_chunk(const LAS unsigned char* sl, f32x4 (&S)[8], float* Orow, int nvalid, int vs, int lane) {
;     const int r = lane & 15, q = lane >> 4;
;     const bf16x8 vfr = *(const LAS bf16x8*)(sl + 16384 + ((vs * 64 + lane) << 4));
;     f32x4 o0 = {0.f, 0.f, 0.f, 0.f}, o1 = {0.f, 0.f, 0.f, 0.f};
;     { const bf16x8 s0 = *(const LAS bf16x8*)(sl + 24576 + (lane << 4)), s1 = *(const LAS bf16x8*)(sl + 24576 + ((64 + lane) << 4));
;       o0 = __builtin_amdgcn_mfma_f32_16x16x32_bf16(s0, vfr, o0, 0, 0, 0); o1 = __builtin_amdgcn_mfma_f32_16x16x32_bf16(s1, vfr, o1, 0, 0, 0); }
; #pragma unroll
;     for (int m = 0; m < 4; ++m) {
;         v4u sw; sw.x = pk2(S[2 * m][0], S[2 * m][1]); sw.y = pk2(S[2 * m][2], S[2 * m][3]); sw.z = pk2(S[2 * m + 1][0], S[2 * m + 1][1]); sw.w = pk2(S[2 * m + 1][2], S[2 * m + 1][3]);
;         const bf16x8 sb = __builtin_bit_cast(bf16x8, sw);
;         const bf16x8 a0 = *(const LAS bf16x8*)(sl + ((m * 64 + lane) << 4)), a1 = *(const LAS bf16x8*)(sl + (((4 + m) * 64 + lane) << 4));
	v_mov_b32_dpp v156, v147 quad_perm:[1,0,3,2] row_mask:0xf bank_mask:0xf
	v_cndmask_b32_e64 v17, v17, v146, s[42:43]
	v_cndmask_b32_e64 v16, v146, v16, s[42:43]
	v_cndmask_b32_e64 v19, v19, v156, s[42:43]
	v_cndmask_b32_e64 v18, v156, v18, s[42:43]
	v_cndmask_b32_e64 v145, v16, v18, s[44:45]
	v_cndmask_b32_e64 v147, v17, v19, s[44:45]
	s_nop 1
	v_mov_b32_dpp v146, v145 quad_perm:[2,3,0,1] row_mask:0xf bank_mask:0xf
	v_mov_b32_dpp v156, v147 quad_perm:[2,3,0,1] row_mask:0xf bank_mask:0xf
	v_cndmask_b32_e64 v18, v18, v146, s[44:45]
	v_cndmask_b32_e64 v16, v146, v16, s[44:45]
	v_cndmask_b32_e64 v19, v19, v156, s[44:45]
	v_cndmask_b32_e64 v17, v156, v17, s[44:45]
	v_cndmask_b32_e64 v145, v20, v21, s[42:43]
	v_cndmask_b32_e64 v147, v22, v23, s[42:43]
	s_nop 1
	v_mov_b32_dpp v146, v145 quad_perm:[1,0,3,2] row_mask:0xf bank_mask:0xf
	v_mov_b32_dpp v156, v147 quad_perm:[1,0,3,2] row_mask:0xf bank_mask:0xf
	v_cndmask_b32_e64 v21, v21, v146, s[42:43]
	v_cndmask_b32_e64 v20, v146, v20, s[42:43]
	v_cndmask_b32_e64 v23, v23, v156, s[42:43]
	v_cndmask_b32_e64 v22, v156, v22, s[42:43]
	v_cndmask_b32_e64 v145, v20, v22, s[44:45]
	v_cndmask_b32_e64 v147, v21, v23, s[44:45]
	s_nop 1
	v_mov_b32_dpp v146, v145 quad_perm:[2,3,0,1] row_mask:0xf bank_mask:0xf
	v_mov_b32_dpp v156, v147 quad_perm:[2,3,0,1] row_mask:0xf bank_mask:0xf
	v_cndmask_b32_e64 v22, v22, v146, s[44:45]
	v_cndmask_b32_e64 v20, v146, v20, s[44:45]
	v_cndmask_b32_e64 v23, v23, v156, s[44:45]
	v_cndmask_b32_e64 v21, v156, v21, s[44:45]
	v_cndmask_b32_e64 v145, v24, v25, s[42:43]
	v_cndmask_b32_e64 v147, v26, v27, s[42:43]
	s_nop 1
	v_mov_b32_dpp v146, v145 quad_perm:[1,0,3,2] row_mask:0xf bank_mask:0xf
	v_mov_b32_dpp v156, v147 quad_perm:[1,0,3,2] row_mask:0xf bank_mask:0xf
	v_cndmask_b32_e64 v25, v25, v146, s[42:43]
	v_cndmask_b32_e64 v24, v146, v24, s[42:43]
	v_cndmask_b32_e64 v27, v27, v156, s[42:43]
	v_cndmask_b32_e64 v26, v156, v26, s[42:43]
	v_cndmask_b32_e64 v145, v24, v26, s[44:45]
	v_cndmask_b32_e64 v147, v25, v27, s[44:45]
	s_nop 1
	v_mov_b32_dpp v146, v145 quad_perm:[2,3,0,1] row_mask:0xf bank_mask:0xf
	v_mov_b32_dpp v156, v147 quad_perm:[2,3,0,1] row_mask:0xf bank_mask:0xf
	v_cndmask_b32_e64 v26, v26, v146, s[44:45]
	v_cndmask_b32_e64 v24, v146, v24, s[44:45]
	v_cndmask_b32_e64 v27, v27, v156, s[44:45]
	v_cndmask_b32_e64 v25, v156, v25, s[44:45]
	v_cndmask_b32_e64 v145, v28, v29, s[42:43]
	v_cndmask_b32_e64 v147, v30, v31, s[42:43]
	s_nop 1
	v_mov_b32_dpp v146, v145 quad_perm:[1,0,3,2] row_mask:0xf bank_mask:0xf
	v_mov_b32_dpp v156, v147 quad_perm:[1,0,3,2] row_mask:0xf bank_mask:0xf
	v_cndmask_b32_e64 v29, v29, v146, s[42:43]
	v_cndmask_b32_e64 v28, v146, v28, s[42:43]
	v_cndmask_b32_e64 v31, v31, v156, s[42:43]
	v_cndmask_b32_e64 v30, v156, v30, s[42:43]
	v_cndmask_b32_e64 v145, v28, v30, s[44:45]
	v_cndmask_b32_e64 v147, v29, v31, s[44:45]
	s_nop 1
	v_mov_b32_dpp v146, v145 quad_perm:[2,3,0,1] row_mask:0xf bank_mask:0xf
	v_mov_b32_dpp v156, v147 quad_perm:[2,3,0,1] row_mask:0xf bank_mask:0xf
	v_cndmask_b32_e64 v30, v30, v146, s[44:45]
	v_cndmask_b32_e64 v28, v146, v28, s[44:45]
	v_cndmask_b32_e64 v31, v31, v156, s[44:45]
	v_cndmask_b32_e64 v29, v156, v29, s[44:45]
	v_cndmask_b32_e64 v145, v32, v33, s[42:43]
	v_cndmask_b32_e64 v147, v34, v35, s[42:43]
	s_nop 1
	v_mov_b32_dpp v146, v145 quad_perm:[1,0,3,2] row_mask:0xf bank_mask:0xf
	v_mov_b32_dpp v156, v147 quad_perm:[1,0,3,2] row_mask:0xf bank_mask:0xf
	v_cndmask_b32_e64 v33, v33, v146, s[42:43]
	v_cndmask_b32_e64 v32, v146, v32, s[42:43]
	v_cndmask_b32_e64 v35, v35, v156, s[42:43]
	v_cndmask_b32_e64 v34, v156, v34, s[42:43]
	v_cndmask_b32_e64 v145, v32, v34, s[44:45]
	v_cndmask_b32_e64 v147, v33, v35, s[44:45]
	s_nop 1
	v_mov_b32_dpp v146, v145 quad_perm:[2,3,0,1] row_mask:0xf bank_mask:0xf
	v_mov_b32_dpp v156, v147 quad_perm:[2,3,0,1] row_mask:0xf bank_mask:0xf
	v_cndmask_b32_e64 v34, v34, v146, s[44:45]
	v_cndmask_b32_e64 v32, v146, v32, s[44:45]
	v_cndmask_b32_e64 v35, v35, v156, s[44:45]
	v_cndmask_b32_e64 v33, v156, v33, s[44:45]
	v_add_u32_e32 v1, 0xd800, v142
	v_add_u32_e32 v2, 0xd800, v143
	v_add_u32_e32 v3, 0xd800, v144
	ds_read_b128 v[164:167], v3 offset:26624
	ds_read_b128 v[168:171], v3 offset:26688
	ds_read_b128 v[172:175], v3 offset:26752
	ds_read_b128 v[176:179], v3 offset:26816
	ds_read_b128 v[180:183], v3 offset:26880
	ds_read_b128 v[184:187], v3 offset:26944
	ds_read_b128 v[148:151], v3 offset:27008
	ds_read_b128 v[152:155], v3 offset:27072
	ds_read_b128 v[84:87], v2 offset:16384
	ds_read_b128 v[88:91], v1 offset:24576
	ds_read_b128 v[92:95], v1 offset:0
	ds_read_b128 v[96:99], v1 offset:1024
	ds_read_b128 v[100:103], v1 offset:2048
	ds_read_b128 v[104:107], v1 offset:3072
	v_cvt_pk_bf16_f32 v68, v4, v5
	v_cvt_pk_bf16_f32 v69, v6, v7
	v_cvt_pk_bf16_f32 v70, v8, v9
	v_cvt_pk_bf16_f32 v71, v10, v11
	v_cvt_pk_bf16_f32 v72, v12, v13
	v_cvt_pk_bf16_f32 v73, v14, v15
	v_cvt_pk_bf16_f32 v74, v16, v17
	v_cvt_pk_bf16_f32 v75, v18, v19
	v_cvt_pk_bf16_f32 v76, v20, v21
	v_cvt_pk_bf16_f32 v77, v22, v23
	v_cvt_pk_bf16_f32 v78, v24, v25
	v_cvt_pk_bf16_f32 v79, v26, v27
	v_cvt_pk_bf16_f32 v80, v28, v29
	v_cvt_pk_bf16_f32 v81, v30, v31
	v_cvt_pk_bf16_f32 v82, v32, v33
	v_cvt_pk_bf16_f32 v83, v34, v35
	s_waitcnt lgkmcnt(6)
; #define LAS __attribute__((address_space(3)))
; __device__ __forceinline__ unsigned pk2(float lo, float hi) { const f32x2_t_ v = {lo, hi}; return __builtin_bit_cast(unsigned, __builtin_convertvector(v, bf16x2_t_)); }
; __device__ __forceinline__ void hg_chunk(const LAS unsigned char* sl, f32x4 (&S)[8], float* Orow, int nvalid, int vs, int lane) {
;     ...
;       o0 = __builtin_amdgcn_mfma_f32_16x16x32_bf16(s0, vfr, o0, 0, 0, 0); o1 = __builtin_amdgcn_mfma_f32_16x16x32_bf16(s1, vfr, o1, 0, 0, 0); }
; #pragma unroll
;     for (int m = 0; m < 4; ++m) {
;         v4u sw; sw.x = pk2(S[2 * m][0], S[2 * m][1]); sw.y = pk2(S[2 * m][2], S[2 * m][3]); sw.z = pk2(S[2 * m + 1][0], S[2 * m + 1][1]); sw.w = pk2(S[2 * m + 1][2], S[2 * m + 1][3]);
;         const bf16x8 sb = __builtin_bit_cast(bf16x8, sw);
;         const bf16x8 a0 = *(const LAS bf16x8*)(sl + ((m * 64 + lane) << 4)), a1 = *(const LAS bf16x8*)(sl + (((4 + m) * 64 + lane) << 4));
;         o0 = __builtin_amdgcn_mfma_f32_16x16x32_bf16(a0, sb, o0, 0, 0, 0); o1 = __builtin_amdgcn_mfma_f32_16x16x32_bf16(a1, sb, o1, 0, 0, 0);
;     }
; #pragma unroll
;     for (int i = 0; i < 4; ++i) { const int c0 = 4 * q + i;
;         if (c0 < nvalid) Orow[(size_t)c0 * DA + 16 * vs + r] = o0[i];
;         if (c0 + 16 < nvalid) Orow[(size_t)(c0 + 16) * DA + 16 * vs + r] = o1[i]; }
; #pragma unroll
;     for (int kb = 0; kb < 8; ++kb) { const f32x4 d = *(const LAS f32x4*)(sl + 26624 + ((16 * kb + 4 * q) << 2));
;         const bf16x8 ke = *(const LAS bf16x8*)(sl + 8192 + ((kb * 64 + lane) << 4));
;         S[kb] = __builtin_amdgcn_mfma_f32_16x16x32_bf16(ke, vfr, S[kb] * d, 0, 0, 0); }
; __device__ __forceinline__ void hg_seq(const Frame& F, unsigned char* ws, const float* s0, float* sout, float* Og, int seq, bool sample, int vs_base, int nvs) {
;     ...
;     if (active) {
; #pragma unroll
;     for (int kb = 0; kb < 8; ++kb)
; #pragma unroll
;         for (int i = 0; i < 4; ++i) sout[((size_t)seq * 128 + 16 * kb + 4 * q + i) * 128 + 16 * vs + r] = S[kb][i];
	v_pk_mul_f32 v[4:5], v[4:5], v[164:165]
	v_pk_mul_f32 v[6:7], v[6:7], v[166:167]
	v_pk_mul_f32 v[8:9], v[8:9], v[168:169]
	v_pk_mul_f32 v[10:11], v[10:11], v[170:171]
	v_pk_mul_f32 v[12:13], v[12:13], v[172:173]
	v_pk_mul_f32 v[14:15], v[14:15], v[174:175]
	v_pk_mul_f32 v[16:17], v[16:17], v[176:177]
	v_pk_mul_f32 v[18:19], v[18:19], v[178:179]
	v_pk_mul_f32 v[20:21], v[20:21], v[180:181]
	v_pk_mul_f32 v[22:23], v[22:23], v[182:183]
	v_pk_mul_f32 v[24:25], v[24:25], v[184:185]
	v_pk_mul_f32 v[26:27], v[26:27], v[186:187]
	v_pk_mul_f32 v[28:29], v[28:29], v[148:149]
	v_pk_mul_f32 v[30:31], v[30:31], v[150:151]
	v_pk_mul_f32 v[32:33], v[32:33], v[152:153]
	v_pk_mul_f32 v[34:35], v[34:35], v[154:155]
	ds_read_b128 v[108:111], v1 offset:8192
	ds_read_b128 v[112:115], v1 offset:9216
	ds_read_b128 v[116:119], v1 offset:10240
	ds_read_b128 v[120:123], v1 offset:11264
	ds_read_b128 v[124:127], v1 offset:12288
	ds_read_b128 v[128:131], v1 offset:13312
	ds_read_b128 v[132:135], v1 offset:14336
	ds_read_b128 v[136:139], v1 offset:15360
	s_waitcnt lgkmcnt(12)
	v_mfma_f32_16x16x32_bf16 v[196:199], v[88:91], v[84:87], 0
	s_waitcnt lgkmcnt(11)
	v_mfma_f32_16x16x32_bf16 v[196:199], v[92:95], v[68:71], v[196:199]
	s_waitcnt lgkmcnt(10)
	v_mfma_f32_16x16x32_bf16 v[196:199], v[96:99], v[72:75], v[196:199]
	s_waitcnt lgkmcnt(9)
	v_mfma_f32_16x16x32_bf16 v[196:199], v[100:103], v[76:79], v[196:199]
	s_waitcnt lgkmcnt(8)
	v_mfma_f32_16x16x32_bf16 v[196:199], v[104:107], v[80:83], v[196:199]
	s_waitcnt lgkmcnt(7)
	v_mfma_f32_16x16x32_bf16 v[4:7], v[108:111], v[84:87], v[4:7]
	s_waitcnt lgkmcnt(6)
	v_mfma_f32_16x16x32_bf16 v[8:11], v[112:115], v[84:87], v[8:11]
	s_waitcnt lgkmcnt(5)
	v_mfma_f32_16x16x32_bf16 v[12:15], v[116:119], v[84:87], v[12:15]
	s_waitcnt lgkmcnt(4)
	v_mfma_f32_16x16x32_bf16 v[16:19], v[120:123], v[84:87], v[16:19]
	s_waitcnt lgkmcnt(3)
	v_mfma_f32_16x16x32_bf16 v[20:23], v[124:127], v[84:87], v[20:23]
	s_waitcnt lgkmcnt(2)
	v_mfma_f32_16x16x32_bf16 v[24:27], v[128:131], v[84:87], v[24:27]
	s_waitcnt lgkmcnt(1)
	v_mfma_f32_16x16x32_bf16 v[28:31], v[132:135], v[84:87], v[28:31]
	s_waitcnt lgkmcnt(0)
	v_mfma_f32_16x16x32_bf16 v[32:35], v[136:139], v[84:87], v[32:35]
	s_mov_b32 exec_hi, 0
	global_store_dword v208, v196, s[12:13]
	global_store_dword v208, v197, s[12:13] offset:2048
	global_store_dword v209, v198, s[12:13]
	global_store_dword v209, v199, s[12:13] offset:2048
	s_mov_b64 exec, -1
	s_add_u32 s12, s12, 0x80000
	s_addc_u32 s13, s13, 0
	s_nop 7
	v_cndmask_b32_e64 v145, v4, v5, s[42:43]
	v_cndmask_b32_e64 v147, v6, v7, s[42:43]
	s_nop 1
	v_mov_b32_dpp v146, v145 quad_perm:[1,0,3,2] row_mask:0xf bank_mask:0xf
	v_mov_b32_dpp v156, v147 quad_perm:[1,0,3,2] row_mask:0xf bank_mask:0xf
	v_cndmask_b32_e64 v5, v5, v146, s[42:43]
	v_cndmask_b32_e64 v4, v146, v4, s[42:43]
	v_cndmask_b32_e64 v7, v7, v156, s[42:43]
	v_cndmask_b32_e64 v6, v156, v6, s[42:43]
	v_cndmask_b32_e64 v145, v4, v6, s[44:45]
	v_cndmask_b32_e64 v147, v5, v7, s[44:45]
	s_nop 1
	v_mov_b32_dpp v146, v145 quad_perm:[2,3,0,1] row_mask:0xf bank_mask:0xf
	v_mov_b32_dpp v156, v147 quad_perm:[2,3,0,1] row_mask:0xf bank_mask:0xf
	v_cndmask_b32_e64 v6, v6, v146, s[44:45]
	v_cndmask_b32_e64 v4, v146, v4, s[44:45]
	v_cndmask_b32_e64 v7, v7, v156, s[44:45]
	v_cndmask_b32_e64 v5, v156, v5, s[44:45]
	v_cndmask_b32_e64 v145, v8, v9, s[42:43]
	v_cndmask_b32_e64 v147, v10, v11, s[42:43]
	s_nop 1
	v_mov_b32_dpp v146, v145 quad_perm:[1,0,3,2] row_mask:0xf bank_mask:0xf
	v_mov_b32_dpp v156, v147 quad_perm:[1,0,3,2] row_mask:0xf bank_mask:0xf
	v_cndmask_b32_e64 v9, v9, v146, s[42:43]
	v_cndmask_b32_e64 v8, v146, v8, s[42:43]
	v_cndmask_b32_e64 v11, v11, v156, s[42:43]
	v_cndmask_b32_e64 v10, v156, v10, s[42:43]
	v_cndmask_b32_e64 v145, v8, v10, s[44:45]
	v_cndmask_b32_e64 v147, v9, v11, s[44:45]
	s_nop 1
	v_mov_b32_dpp v146, v145 quad_perm:[2,3,0,1] row_mask:0xf bank_mask:0xf
	v_mov_b32_dpp v156, v147 quad_perm:[2,3,0,1] row_mask:0xf bank_mask:0xf
	v_cndmask_b32_e64 v10, v10, v146, s[44:45]
	v_cndmask_b32_e64 v8, v146, v8, s[44:45]
	v_cndmask_b32_e64 v11, v11, v156, s[44:45]
	v_cndmask_b32_e64 v9, v156, v9, s[44:45]
	v_cndmask_b32_e64 v145, v12, v13, s[42:43]
	v_cndmask_b32_e64 v147, v14, v15, s[42:43]
	s_nop 1
	v_mov_b32_dpp v146, v145 quad_perm:[1,0,3,2] row_mask:0xf bank_mask:0xf
	v_mov_b32_dpp v156, v147 quad_perm:[1,0,3,2] row_mask:0xf bank_mask:0xf
	v_cndmask_b32_e64 v13, v13, v146, s[42:43]
	v_cndmask_b32_e64 v12, v146, v12, s[42:43]
	v_cndmask_b32_e64 v15, v15, v156, s[42:43]
	v_cndmask_b32_e64 v14, v156, v14, s[42:43]
	v_cndmask_b32_e64 v145, v12, v14, s[44:45]
	v_cndmask_b32_e64 v147, v13, v15, s[44:45]
	s_nop 1
	v_mov_b32_dpp v146, v145 quad_perm:[2,3,0,1] row_mask:0xf bank_mask:0xf
	v_mov_b32_dpp v156, v147 quad_perm:[2,3,0,1] row_mask:0xf bank_mask:0xf
; __device__ __forceinline__ void hg_seq(const Frame& F, unsigned char* ws, const float* s0, float* sout, float* Og, int seq, bool sample, int vs_base, int nvs) {
;     ...
;     if (active) {
; #pragma unroll
;     for (int kb = 0; kb < 8; ++kb)
; #pragma unroll
;         for (int i = 0; i < 4; ++i) sout[((size_t)seq * 128 + 16 * kb + 4 * q + i) * 128 + 16 * vs + r] = S[kb][i];
;     }
	v_cndmask_b32_e64 v14, v14, v146, s[44:45]
	v_cndmask_b32_e64 v12, v146, v12, s[44:45]
	v_cndmask_b32_e64 v15, v15, v156, s[44:45]
	v_cndmask_b32_e64 v13, v156, v13, s[44:45]
	v_cndmask_b32_e64 v145, v16, v17, s[42:43]
	v_cndmask_b32_e64 v147, v18, v19, s[42:43]
	s_nop 1
	v_mov_b32_dpp v146, v145 quad_perm:[1,0,3,2] row_mask:0xf bank_mask:0xf
	v_mov_b32_dpp v156, v147 quad_perm:[1,0,3,2] row_mask:0xf bank_mask:0xf
	v_cndmask_b32_e64 v17, v17, v146, s[42:43]
	v_cndmask_b32_e64 v16, v146, v16, s[42:43]
	v_cndmask_b32_e64 v19, v19, v156, s[42:43]
	v_cndmask_b32_e64 v18, v156, v18, s[42:43]
	v_cndmask_b32_e64 v145, v16, v18, s[44:45]
	v_cndmask_b32_e64 v147, v17, v19, s[44:45]
	s_nop 1
	v_mov_b32_dpp v146, v145 quad_perm:[2,3,0,1] row_mask:0xf bank_mask:0xf
	v_mov_b32_dpp v156, v147 quad_perm:[2,3,0,1] row_mask:0xf bank_mask:0xf
	v_cndmask_b32_e64 v18, v18, v146, s[44:45]
	v_cndmask_b32_e64 v16, v146, v16, s[44:45]
	v_cndmask_b32_e64 v19, v19, v156, s[44:45]
	v_cndmask_b32_e64 v17, v156, v17, s[44:45]
	v_cndmask_b32_e64 v145, v20, v21, s[42:43]
	v_cndmask_b32_e64 v147, v22, v23, s[42:43]
	s_nop 1
	v_mov_b32_dpp v146, v145 quad_perm:[1,0,3,2] row_mask:0xf bank_mask:0xf
	v_mov_b32_dpp v156, v147 quad_perm:[1,0,3,2] row_mask:0xf bank_mask:0xf
	v_cndmask_b32_e64 v21, v21, v146, s[42:43]
	v_cndmask_b32_e64 v20, v146, v20, s[42:43]
	v_cndmask_b32_e64 v23, v23, v156, s[42:43]
	v_cndmask_b32_e64 v22, v156, v22, s[42:43]
	v_cndmask_b32_e64 v145, v20, v22, s[44:45]
	v_cndmask_b32_e64 v147, v21, v23, s[44:45]
	s_nop 1
	v_mov_b32_dpp v146, v145 quad_perm:[2,3,0,1] row_mask:0xf bank_mask:0xf
	v_mov_b32_dpp v156, v147 quad_perm:[2,3,0,1] row_mask:0xf bank_mask:0xf
	v_cndmask_b32_e64 v22, v22, v146, s[44:45]
	v_cndmask_b32_e64 v20, v146, v20, s[44:45]
	v_cndmask_b32_e64 v23, v23, v156, s[44:45]
	v_cndmask_b32_e64 v21, v156, v21, s[44:45]
	v_cndmask_b32_e64 v145, v24, v25, s[42:43]
	v_cndmask_b32_e64 v147, v26, v27, s[42:43]
	s_nop 1
	v_mov_b32_dpp v146, v145 quad_perm:[1,0,3,2] row_mask:0xf bank_mask:0xf
	v_mov_b32_dpp v156, v147 quad_perm:[1,0,3,2] row_mask:0xf bank_mask:0xf
	v_cndmask_b32_e64 v25, v25, v146, s[42:43]
	v_cndmask_b32_e64 v24, v146, v24, s[42:43]
	v_cndmask_b32_e64 v27, v27, v156, s[42:43]
	v_cndmask_b32_e64 v26, v156, v26, s[42:43]
	v_cndmask_b32_e64 v145, v24, v26, s[44:45]
	v_cndmask_b32_e64 v147, v25, v27, s[44:45]
	s_nop 1
	v_mov_b32_dpp v146, v145 quad_perm:[2,3,0,1] row_mask:0xf bank_mask:0xf
	v_mov_b32_dpp v156, v147 quad_perm:[2,3,0,1] row_mask:0xf bank_mask:0xf
	v_cndmask_b32_e64 v26, v26, v146, s[44:45]
	v_cndmask_b32_e64 v24, v146, v24, s[44:45]
	v_cndmask_b32_e64 v27, v27, v156, s[44:45]
	v_cndmask_b32_e64 v25, v156, v25, s[44:45]
	v_cndmask_b32_e64 v145, v28, v29, s[42:43]
	v_cndmask_b32_e64 v147, v30, v31, s[42:43]
	s_nop 1
	v_mov_b32_dpp v146, v145 quad_perm:[1,0,3,2] row_mask:0xf bank_mask:0xf
	v_mov_b32_dpp v156, v147 quad_perm:[1,0,3,2] row_mask:0xf bank_mask:0xf
	v_cndmask_b32_e64 v29, v29, v146, s[42:43]
	v_cndmask_b32_e64 v28, v146, v28, s[42:43]
	v_cndmask_b32_e64 v31, v31, v156, s[42:43]
	v_cndmask_b32_e64 v30, v156, v30, s[42:43]
	v_cndmask_b32_e64 v145, v28, v30, s[44:45]
	v_cndmask_b32_e64 v147, v29, v31, s[44:45]
	s_nop 1
	v_mov_b32_dpp v146, v145 quad_perm:[2,3,0,1] row_mask:0xf bank_mask:0xf
	v_mov_b32_dpp v156, v147 quad_perm:[2,3,0,1] row_mask:0xf bank_mask:0xf
	v_cndmask_b32_e64 v30, v30, v146, s[44:45]
	v_cndmask_b32_e64 v28, v146, v28, s[44:45]
	v_cndmask_b32_e64 v31, v31, v156, s[44:45]
	v_cndmask_b32_e64 v29, v156, v29, s[44:45]
	v_cndmask_b32_e64 v145, v32, v33, s[42:43]
	v_cndmask_b32_e64 v147, v34, v35, s[42:43]
	s_nop 1
	v_mov_b32_dpp v146, v145 quad_perm:[1,0,3,2] row_mask:0xf bank_mask:0xf
	v_mov_b32_dpp v156, v147 quad_perm:[1,0,3,2] row_mask:0xf bank_mask:0xf
	v_cndmask_b32_e64 v33, v33, v146, s[42:43]
	v_cndmask_b32_e64 v32, v146, v32, s[42:43]
	v_cndmask_b32_e64 v35, v35, v156, s[42:43]
	v_cndmask_b32_e64 v34, v156, v34, s[42:43]
	v_cndmask_b32_e64 v145, v32, v34, s[44:45]
	v_cndmask_b32_e64 v147, v33, v35, s[44:45]
	s_nop 1
	v_mov_b32_dpp v146, v145 quad_perm:[2,3,0,1] row_mask:0xf bank_mask:0xf
	v_mov_b32_dpp v156, v147 quad_perm:[2,3,0,1] row_mask:0xf bank_mask:0xf
	v_cndmask_b32_e64 v34, v34, v146, s[44:45]
	v_cndmask_b32_e64 v32, v146, v32, s[44:45]
	v_cndmask_b32_e64 v35, v35, v156, s[44:45]
	v_cndmask_b32_e64 v33, v156, v33, s[44:45]
	global_store_dwordx4 v200, v[4:7], s[10:11]
	global_store_dwordx4 v201, v[8:11], s[10:11]
	global_store_dwordx4 v202, v[12:15], s[10:11]
	global_store_dwordx4 v203, v[16:19], s[10:11]
	global_store_dwordx4 v204, v[20:23], s[10:11]
	global_store_dwordx4 v205, v[24:27], s[10:11]
	global_store_dwordx4 v206, v[28:31], s[10:11]
	global_store_dwordx4 v207, v[32:35], s[10:11]
	s_add_u32 s10, s10, s34
	s_addc_u32 s11, s11, 0
	s_waitcnt lgkmcnt(0)
	s_barrier
